# v36 + LN1/router token loop: b_expert/b_group held in VGPRs loaded once per 64-token item (removes 5 dependent global loads+vmcnt(0) per token in the scalar router code); next-token prefetch issued af
# speedup vs baseline: 1.0143x; 1.0042x over previous
.LBB0_548:
	s_barrier
	s_and_saveexec_b64 s[0:1], s[6:7]
	ds_write_b32 v99, v61
	s_or_b64 exec, exec, s[0:1]
	s_lshl_b32 s4, s2, 6
	s_ashr_i32 s5, s4, 31
	v_lshl_add_u64 v[82:83], s[4:5], 0, v[58:59]
	v_lshlrev_b64 v[0:1], 12, v[82:83]
	v_lshl_add_u64 v[0:1], v[62:63], 0, v[0:1]
	v_lshlrev_b64 v[2:3], 11, v[82:83]
	v_lshl_add_u64 v[2:3], v[64:65], 0, v[2:3]
	global_load_dwordx4 v[28:31], v[0:1], off
	global_load_dwordx4 v[20:23], v[0:1], off offset:1024
	global_load_dwordx4 v[24:27], v[0:1], off offset:2048
	global_load_dwordx4 v[16:19], v[0:1], off offset:3072
	global_load_dwordx2 v[84:85], v[2:3], off
	global_load_dwordx2 v[88:89], v[2:3], off offset:512
	global_load_dwordx2 v[90:91], v[2:3], off offset:1024
	global_load_dwordx2 v[92:93], v[2:3], off offset:1536
	global_load_dword v162, v61, s[72:73] offset:0
	global_load_dword v163, v61, s[72:73] offset:4
	global_load_dword v164, v61, s[72:73] offset:8
	global_load_dword v165, v61, s[72:73] offset:12
	global_load_dword v166, v61, s[72:73] offset:16
	global_load_dword v167, v61, s[72:73] offset:20
	global_load_dword v168, v61, s[72:73] offset:24
	global_load_dword v169, v61, s[72:73] offset:28
	global_load_dword v170, v61, s[72:73] offset:32
	global_load_dword v171, v61, s[72:73] offset:36
	global_load_dword v172, v61, s[72:73] offset:40
	global_load_dword v173, v61, s[72:73] offset:44
	global_load_dword v174, v61, s[72:73] offset:48
	global_load_dword v175, v61, s[72:73] offset:52
	global_load_dword v176, v61, s[72:73] offset:56
	global_load_dword v177, v61, s[72:73] offset:60
	global_load_dwordx4 v[178:181], v61, s[68:69] offset:0
	v_writelane_b32 v236, s2, 2
	s_mov_b32 s0, s4
	s_ashr_i32 s13, s12, 31
	v_writelane_b32 v236, s0, 4
	v_lshl_add_u64 v[0:1], v[58:59], 0, s[12:13]
	v_lshlrev_b64 v[0:1], 11, v[0:1]
	v_writelane_b32 v236, s1, 5
	s_mov_b32 s0, s12
	v_writelane_b32 v236, s0, 6
	v_lshl_add_u64 v[86:87], v[80:81], 0, v[0:1]
	s_mov_b32 s7, 0
	v_mov_b32_e32 v121, v115
	v_writelane_b32 v236, s1, 7
	s_branch .LBB0_552
.LBB0_551:
	s_or_b64 exec, exec, s[26:27]
	s_mov_b64 s[0:1], 0x800
	v_add_u32_e32 v121, 4, v121
	v_lshl_add_u64 v[86:87], v[86:87], 0, s[0:1]
	s_cmp_eq_u32 s23, 16
	s_mov_b32 s7, s23
	s_waitcnt vmcnt(0)
	v_mov_b64_e32 v[28:29], v[0:1]
	v_mov_b64_e32 v[30:31], v[2:3]
	v_mov_b64_e32 v[20:21], v[4:5]
	v_mov_b64_e32 v[22:23], v[6:7]
	v_mov_b64_e32 v[24:25], v[8:9]
	v_mov_b64_e32 v[26:27], v[10:11]
	v_mov_b64_e32 v[16:17], v[12:13]
	v_mov_b64_e32 v[18:19], v[14:15]
	s_cbranch_scc1 .LBB0_586
.LBB0_552:
	s_add_i32 s23, s7, 1
	s_waitcnt vmcnt(0)
	v_mov_b64_e32 v[38:39], v[84:85]
	v_mov_b64_e32 v[32:33], v[92:93]
	v_mov_b64_e32 v[34:35], v[90:91]
	v_mov_b64_e32 v[36:37], v[88:89]
	v_lshlrev_b32_e32 v40, 16, v38
	v_and_b32_e32 v41, 0xffff0000, v38
	v_lshlrev_b32_e32 v38, 16, v39
	v_and_b32_e32 v39, 0xffff0000, v39
	v_lshlrev_b32_e32 v54, 16, v36
	v_and_b32_e32 v55, 0xffff0000, v36
	v_lshlrev_b32_e32 v94, 16, v37
	v_and_b32_e32 v95, 0xffff0000, v37
	v_lshlrev_b32_e32 v96, 16, v34
	v_and_b32_e32 v97, 0xffff0000, v34
	v_lshlrev_b32_e32 v100, 16, v35
	v_and_b32_e32 v101, 0xffff0000, v35
	v_lshlrev_b32_e32 v102, 16, v32
	v_and_b32_e32 v103, 0xffff0000, v32
	v_lshlrev_b32_e32 v104, 16, v33
	v_and_b32_e32 v105, 0xffff0000, v33
	v_pk_fma_f32 v[106:107], v[30:31], s[22:23], v[38:39] op_sel_hi:[1,0,1]
	global_load_dwordx4 v[30:33], v[66:67], off
	global_load_dwordx4 v[34:37], v[68:69], off
	v_pk_fma_f32 v[28:29], v[28:29], s[22:23], v[40:41] op_sel_hi:[1,0,1]
	v_pk_fma_f32 v[20:21], v[20:21], s[22:23], v[54:55] op_sel_hi:[1,0,1]
	v_add_f32_e32 v38, v28, v29
	v_add_f32_e32 v38, v38, v106
	v_pk_fma_f32 v[22:23], v[22:23], s[22:23], v[94:95] op_sel_hi:[1,0,1]
	v_add_f32_e32 v54, v20, v21
	v_pk_fma_f32 v[24:25], v[24:25], s[22:23], v[96:97] op_sel_hi:[1,0,1]
	v_add_f32_e32 v38, v107, v38
	v_add_f32_e32 v54, v54, v22
	v_pk_fma_f32 v[26:27], v[26:27], s[22:23], v[100:101] op_sel_hi:[1,0,1]
	v_add_f32_e32 v55, v24, v25
	v_add_f32_e32 v98, 0, v38
	v_add_f32_e32 v54, v23, v54
	v_add_f32_e32 v55, v55, v26
	v_add_f32_e32 v54, v98, v54
	v_add_f32_e32 v55, v27, v55
	v_pk_fma_f32 v[16:17], v[16:17], s[22:23], v[102:103] op_sel_hi:[1,0,1]
	v_add_f32_e32 v54, v54, v55
	v_pk_fma_f32 v[18:19], v[18:19], s[22:23], v[104:105] op_sel_hi:[1,0,1]
	v_add_f32_e32 v55, v16, v17
	v_add_f32_e32 v55, v55, v18
	v_add_f32_e32 v55, v19, v55
	v_add_f32_e32 v54, v54, v55
	ds_read_b128 v[38:41], v60
	ds_read_b128 v[42:45], v60 offset:4096
	ds_read_b128 v[46:49], v60 offset:8192
	ds_read_b128 v[50:53], v60 offset:12288
	ds_read_b128 v[108:111], v60 offset:16384
	ds_read_b128 v[122:125], v60 offset:20480
	ds_read_b128 v[130:133], v60 offset:24576
	ds_read_b128 v[134:137], v60 offset:28672
	ds_read_b128 v[138:141], v60 offset:32768
	ds_read_b128 v[142:145], v60 offset:36864
	ds_read_b128 v[146:149], v60 offset:40960
	ds_read_b128 v[150:153], v60 offset:45056
	ds_read_b128 v[154:157], v60 offset:49152
	v_add_f32_dpp v54, v54, v54 quad_perm:[1,0,3,2] row_mask:0xf bank_mask:0xf bound_ctrl:1
	s_nop 1
	v_add_f32_dpp v54, v54, v54 quad_perm:[2,3,0,1] row_mask:0xf bank_mask:0xf bound_ctrl:1
	s_nop 1
	v_add_f32_dpp v54, v54, v54 row_half_mirror row_mask:0xf bank_mask:0xf bound_ctrl:1
	s_nop 1
	v_add_f32_dpp v54, v54, v54 row_mirror row_mask:0xf bank_mask:0xf bound_ctrl:1
	s_nop 0
	v_readlane_b32 s2, v54, 16
	v_readlane_b32 s4, v54, 48
	v_readlane_b32 s0, v54, 0
	v_readlane_b32 s1, v54, 32
	v_mov_b32_e32 v54, s2
	v_mov_b32_e32 v55, s4
	v_pk_add_f32 v[54:55], s[0:1], v[54:55]
	s_nop 0
	v_add_f32_e32 v54, v54, v55
	v_mul_f32_e32 v54, 0x3a800000, v54
	v_pk_add_f32 v[28:29], v[28:29], v[54:55] op_sel_hi:[1,0] neg_lo:[0,1] neg_hi:[0,1]
	v_pk_add_f32 v[126:127], v[106:107], v[54:55] op_sel_hi:[1,0] neg_lo:[0,1] neg_hi:[0,1]
	v_pk_mul_f32 v[104:105], v[28:29], v[28:29]
	v_pk_mul_f32 v[106:107], v[126:127], v[126:127]
	v_pk_add_f32 v[158:159], v[20:21], v[54:55] op_sel_hi:[1,0] neg_lo:[0,1] neg_hi:[0,1]
	v_pk_add_f32 v[160:161], v[22:23], v[54:55] op_sel_hi:[1,0] neg_lo:[0,1] neg_hi:[0,1]
	v_pk_add_f32 v[100:101], v[24:25], v[54:55] op_sel_hi:[1,0] neg_lo:[0,1] neg_hi:[0,1]
	v_pk_add_f32 v[102:103], v[26:27], v[54:55] op_sel_hi:[1,0] neg_lo:[0,1] neg_hi:[0,1]
	v_pk_add_f32 v[94:95], v[16:17], v[54:55] op_sel_hi:[1,0] neg_lo:[0,1] neg_hi:[0,1]
	v_pk_add_f32 v[96:97], v[18:19], v[54:55] op_sel_hi:[1,0] neg_lo:[0,1] neg_hi:[0,1]
	v_add_f32_e32 v54, v104, v105
	v_add_f32_e32 v54, v106, v54
	v_pk_mul_f32 v[20:21], v[158:159], v[158:159]
	v_add_f32_e32 v54, v107, v54
	v_add_f32_e32 v20, v20, v54
	v_pk_mul_f32 v[22:23], v[160:161], v[160:161]
	v_add_f32_e32 v20, v21, v20
	v_add_f32_e32 v20, v22, v20
	v_pk_mul_f32 v[24:25], v[100:101], v[100:101]
	v_add_f32_e32 v20, v23, v20
	v_add_f32_e32 v20, v24, v20
	v_pk_mul_f32 v[26:27], v[102:103], v[102:103]
	v_add_f32_e32 v20, v25, v20
	v_add_f32_e32 v20, v26, v20
	v_pk_mul_f32 v[16:17], v[94:95], v[94:95]
	v_add_f32_e32 v20, v27, v20
	v_add_f32_e32 v16, v16, v20
	v_pk_mul_f32 v[18:19], v[96:97], v[96:97]
	v_add_f32_e32 v16, v17, v16
	v_add_f32_e32 v16, v18, v16
	v_add_f32_e32 v16, v19, v16
	s_nop 1
	v_add_f32_dpp v16, v16, v16 quad_perm:[1,0,3,2] row_mask:0xf bank_mask:0xf bound_ctrl:1
	s_nop 1
	v_add_f32_dpp v16, v16, v16 quad_perm:[2,3,0,1] row_mask:0xf bank_mask:0xf bound_ctrl:1
	s_nop 1
	v_add_f32_dpp v16, v16, v16 row_half_mirror row_mask:0xf bank_mask:0xf bound_ctrl:1
	s_nop 1
	v_add_f32_dpp v16, v16, v16 row_mirror row_mask:0xf bank_mask:0xf bound_ctrl:1
	s_nop 0
	v_readlane_b32 s2, v16, 16
	v_readlane_b32 s4, v16, 48
	v_readlane_b32 s0, v16, 0
	v_readlane_b32 s1, v16, 32
	v_mov_b32_e32 v16, s2
	v_mov_b32_e32 v17, s4
	v_pk_add_f32 v[16:17], s[0:1], v[16:17]
	s_mov_b32 s0, 0x800000
	v_add_f32_e32 v16, v16, v17
	v_fmamk_f32 v16, v16, 0x3a800000, v116
	v_cmp_gt_f32_e32 vcc, s0, v16
	v_mul_f32_e32 v17, 0x4b800000, v16
	s_nop 0
	v_cndmask_b32_e32 v16, v16, v17, vcc
	v_rsq_f32_e32 v54, v16
	ds_read_b128 v[16:19], v60 offset:53248
	ds_read_b128 v[20:23], v60 offset:57344
	ds_read_b128 v[24:27], v60 offset:61440
	v_mul_f32_e32 v55, 0x45800000, v54
	v_cndmask_b32_e32 v98, v54, v55, vcc
	v_pk_mul_f32 v[28:29], v[28:29], v[98:99] op_sel_hi:[1,0]
	s_waitcnt vmcnt(0)
	v_pk_fma_f32 v[106:107], v[30:31], v[28:29], v[34:35]
	v_pk_mul_f32 v[28:29], v[126:127], v[98:99] op_sel_hi:[1,0]
	s_waitcnt lgkmcnt(2)
	v_mul_f32_e32 v17, v107, v17
	v_pk_fma_f32 v[104:105], v[32:33], v[28:29], v[36:37]
	v_cvt_pk_bf16_f32 v28, v106, v107
	v_cvt_pk_bf16_f32 v29, v104, v105
	global_store_dwordx2 v[86:87], v[28:29], off offset:-1024
	v_mul_f32_e32 v28, v39, v107
	v_fmac_f32_e32 v28, v38, v106
	global_load_dwordx4 v[32:35], v[66:67], off offset:1024
	global_load_dwordx4 v[36:39], v[68:69], off offset:1024
	v_fmac_f32_e32 v28, v104, v40
	v_fmac_f32_e32 v28, v105, v41
	v_add_f32_e32 v54, 0, v28
	v_mul_f32_e32 v28, v107, v43
	v_fmac_f32_e32 v28, v106, v42
	v_fmac_f32_e32 v28, v104, v44
	v_fmac_f32_e32 v28, v105, v45
	v_add_f32_e32 v55, 0, v28
	v_mul_f32_e32 v28, v107, v47
	v_fmac_f32_e32 v28, v106, v46
	v_fmac_f32_e32 v28, v104, v48
	v_fmac_f32_e32 v28, v105, v49
	v_add_f32_e32 v46, 0, v28
	v_mul_f32_e32 v28, v107, v51
	v_fmac_f32_e32 v28, v106, v50
	v_fmac_f32_e32 v28, v104, v52
	v_fmac_f32_e32 v28, v105, v53
	v_add_f32_e32 v45, 0, v28
	v_mul_f32_e32 v28, v107, v109
	v_fmac_f32_e32 v28, v106, v108
	v_fmac_f32_e32 v28, v104, v110
	v_fmac_f32_e32 v28, v105, v111
	v_add_f32_e32 v44, 0, v28
	v_mul_f32_e32 v28, v107, v123
	v_fmac_f32_e32 v28, v106, v122
	v_fmac_f32_e32 v28, v104, v124
	v_fmac_f32_e32 v28, v105, v125
	v_add_f32_e32 v53, 0, v28
	v_mul_f32_e32 v28, v107, v131
	v_fmac_f32_e32 v28, v106, v130
	v_fmac_f32_e32 v28, v104, v132
	v_fmac_f32_e32 v28, v105, v133
	v_add_f32_e32 v52, 0, v28
	v_mul_f32_e32 v28, v107, v135
	v_fmac_f32_e32 v28, v106, v134
	v_fmac_f32_e32 v28, v104, v136
	v_fmac_f32_e32 v28, v105, v137
	v_add_f32_e32 v51, 0, v28
	v_mul_f32_e32 v28, v107, v139
	v_fmac_f32_e32 v28, v106, v138
	v_fmac_f32_e32 v28, v104, v140
	v_fmac_f32_e32 v28, v105, v141
	v_add_f32_e32 v50, 0, v28
	v_mul_f32_e32 v28, v107, v143
	v_fmac_f32_e32 v28, v106, v142
	v_fmac_f32_e32 v28, v104, v144
	v_fmac_f32_e32 v28, v105, v145
	v_add_f32_e32 v49, 0, v28
	v_mul_f32_e32 v28, v107, v147
	v_fmac_f32_e32 v28, v106, v146
	v_fmac_f32_e32 v28, v104, v148
	v_fmac_f32_e32 v28, v105, v149
	v_add_f32_e32 v48, 0, v28
	v_mul_f32_e32 v28, v107, v151
	v_fmac_f32_e32 v17, v106, v16
	s_waitcnt lgkmcnt(1)
	v_mul_f32_e32 v16, v107, v21
	v_fmac_f32_e32 v28, v106, v150
	v_fmac_f32_e32 v16, v106, v20
	v_fmac_f32_e32 v28, v104, v152
	v_fmac_f32_e32 v16, v104, v22
	v_fmac_f32_e32 v28, v105, v153
	v_fmac_f32_e32 v16, v105, v23
	v_add_f32_e32 v131, 0, v28
	v_mul_f32_e32 v28, v107, v155
	v_add_f32_e32 v122, 0, v16
	s_waitcnt lgkmcnt(0)
	v_mul_f32_e32 v16, v107, v25
	v_fmac_f32_e32 v28, v106, v154
	v_fmac_f32_e32 v16, v106, v24
	v_fmac_f32_e32 v28, v104, v156
	v_fmac_f32_e32 v17, v104, v18
	v_fmac_f32_e32 v16, v104, v26
	v_fmac_f32_e32 v28, v105, v157
	v_fmac_f32_e32 v17, v105, v19
	v_fmac_f32_e32 v16, v105, v27
	v_pk_mul_f32 v[40:41], v[158:159], v[98:99] op_sel_hi:[1,0]
	v_add_f32_e32 v125, 0, v28
	v_add_f32_e32 v124, 0, v17
	v_add_f32_e32 v123, 0, v16
	global_load_dwordx4 v[16:19], v[72:73], off offset:48
	global_load_dwordx4 v[20:23], v[72:73], off offset:32
	global_load_dwordx4 v[24:27], v[72:73], off offset:16
	global_load_dwordx4 v[28:31], v[72:73], off
	s_waitcnt vmcnt(4)
	v_pk_fma_f32 v[108:109], v[40:41], v[32:33], v[36:37]
	ds_read_b128 v[40:43], v60 offset:1024
	ds_read_b128 v[134:137], v60 offset:21504
	v_pk_mul_f32 v[32:33], v[160:161], v[98:99] op_sel_hi:[1,0]
	ds_read_b128 v[142:145], v60 offset:29696
	v_pk_fma_f32 v[110:111], v[32:33], v[34:35], v[38:39]
	s_waitcnt lgkmcnt(2)
	v_mul_f32_e32 v36, v109, v41
	v_cvt_pk_bf16_f32 v32, v108, v109
	v_cvt_pk_bf16_f32 v33, v110, v111
	v_fmac_f32_e32 v36, v108, v40
	global_store_dwordx2 v[86:87], v[32:33], off offset:-512
	ds_read_b128 v[32:35], v60 offset:5120
	v_fmac_f32_e32 v36, v110, v42
	v_fmac_f32_e32 v36, v111, v43
	v_add_f32_e32 v126, v54, v36
	s_waitcnt lgkmcnt(2)
	v_mul_f32_e32 v54, v109, v135
	s_waitcnt lgkmcnt(1)
	v_mul_f32_e32 v135, v109, v143
	v_fmac_f32_e32 v135, v108, v142
	v_fmac_f32_e32 v135, v110, v144
	v_fmac_f32_e32 v135, v111, v145
	ds_read_b128 v[144:147], v60 offset:50176
	s_waitcnt lgkmcnt(1)
	v_mul_f32_e32 v33, v109, v33
	v_fmac_f32_e32 v33, v108, v32
	v_fmac_f32_e32 v33, v110, v34
	v_fmac_f32_e32 v33, v111, v35
	ds_read_b128 v[36:39], v60 offset:9216
	v_add_f32_e32 v127, v55, v33
	ds_read_b128 v[32:35], v60 offset:13312
	ds_read_b128 v[40:43], v60 offset:17408
	ds_read_b128 v[138:141], v60 offset:25600
	v_fmac_f32_e32 v54, v108, v134
	v_fmac_f32_e32 v54, v110, v136
	s_waitcnt lgkmcnt(3)
	v_mul_f32_e32 v37, v109, v37
	s_waitcnt lgkmcnt(2)
	v_mul_f32_e32 v33, v109, v33
	v_fmac_f32_e32 v54, v111, v137
	v_fmac_f32_e32 v37, v108, v36
	v_fmac_f32_e32 v33, v108, v32
	v_add_f32_e32 v133, v53, v54
	s_waitcnt lgkmcnt(0)
	v_mul_f32_e32 v53, v109, v139
	v_fmac_f32_e32 v37, v110, v38
	v_fmac_f32_e32 v33, v110, v34
	v_mul_f32_e32 v41, v109, v41
	v_fmac_f32_e32 v53, v108, v138
	v_fmac_f32_e32 v37, v111, v39
	v_fmac_f32_e32 v33, v111, v35
	v_fmac_f32_e32 v41, v108, v40
	v_fmac_f32_e32 v53, v110, v140
	v_add_f32_e32 v129, v46, v37
	v_add_f32_e32 v130, v45, v33
	global_load_dwordx4 v[32:35], v[74:75], off
	global_load_dwordx4 v[36:39], v[74:75], off offset:16
	v_fmac_f32_e32 v41, v110, v42
	v_fmac_f32_e32 v53, v111, v141
	v_fmac_f32_e32 v41, v111, v43
	v_add_f32_e32 v134, v52, v53
	ds_read_b128 v[52:55], v60 offset:33792
	ds_read_b128 v[138:141], v60 offset:37888
	v_add_f32_e32 v132, v44, v41
	global_load_dwordx4 v[40:43], v[74:75], off offset:32
	global_load_dwordx4 v[44:47], v[74:75], off offset:48
	v_add_f32_e32 v135, v51, v135
	s_waitcnt lgkmcnt(1)
	v_mul_f32_e32 v51, v109, v53
	v_fmac_f32_e32 v51, v108, v52
	v_fmac_f32_e32 v51, v110, v54
	v_fmac_f32_e32 v51, v111, v55
	v_add_f32_e32 v136, v50, v51
	ds_read_b128 v[50:53], v60 offset:41984
	s_waitcnt lgkmcnt(1)
	v_mul_f32_e32 v54, v109, v139
	v_fmac_f32_e32 v54, v108, v138
	v_fmac_f32_e32 v54, v110, v140
	v_fmac_f32_e32 v54, v111, v141
	v_add_f32_e32 v137, v49, v54
	ds_read_b128 v[140:143], v60 offset:46080
	s_waitcnt lgkmcnt(1)
	v_mul_f32_e32 v49, v109, v51
	v_fmac_f32_e32 v49, v108, v50
	v_fmac_f32_e32 v49, v110, v52
	v_fmac_f32_e32 v49, v111, v53
	v_add_f32_e32 v138, v48, v49
	global_load_dwordx4 v[48:51], v[66:67], off offset:2048
	global_load_dwordx4 v[52:55], v[68:69], off offset:2048
	s_waitcnt lgkmcnt(0)
	v_mul_f32_e32 v139, v109, v141
	v_fmac_f32_e32 v139, v108, v140
	v_fmac_f32_e32 v139, v110, v142
	v_fmac_f32_e32 v139, v111, v143
	ds_read_b128 v[140:143], v60 offset:54272
	v_add_f32_e32 v131, v131, v139
	v_mul_f32_e32 v139, v109, v145
	v_fmac_f32_e32 v139, v108, v144
	v_fmac_f32_e32 v139, v110, v146
	v_fmac_f32_e32 v139, v111, v147
	ds_read_b128 v[144:147], v60 offset:58368
	v_add_f32_e32 v139, v125, v139
	s_waitcnt lgkmcnt(1)
	v_mul_f32_e32 v125, v109, v141
	v_fmac_f32_e32 v125, v108, v140
	v_fmac_f32_e32 v125, v110, v142
	v_fmac_f32_e32 v125, v111, v143
	ds_read_b128 v[140:143], v60 offset:62464
	v_add_f32_e32 v148, v124, v125
	s_waitcnt lgkmcnt(1)
	v_mul_f32_e32 v124, v109, v145
	v_fmac_f32_e32 v124, v108, v144
	v_fmac_f32_e32 v124, v110, v146
	v_fmac_f32_e32 v124, v111, v147
	v_add_f32_e32 v144, v122, v124
	s_waitcnt lgkmcnt(0)
	v_mul_f32_e32 v122, v109, v141
	v_fmac_f32_e32 v122, v108, v140
	v_fmac_f32_e32 v122, v110, v142
	v_fmac_f32_e32 v122, v111, v143
	v_add_f32_e32 v142, v123, v122
	v_mov_b32_e32 v122, v106
	v_mov_b32_e32 v123, v108
	v_mov_b32_e32 v108, v107
	s_waitcnt vmcnt(8)
	v_mov_b32_e32 v106, v24
	s_waitcnt vmcnt(7)
	v_mov_b32_e32 v124, v28
	v_mov_b32_e32 v140, v20
	s_waitcnt vmcnt(5)
	v_mov_b32_e32 v125, v32
	s_waitcnt vmcnt(4)
	v_mov_b32_e32 v107, v36
	v_pk_mul_f32 v[106:107], v[108:109], v[106:107]
	v_mov_b32_e32 v36, v25
	v_pk_fma_f32 v[106:107], v[122:123], v[124:125], v[106:107]
	v_mov_b32_e32 v124, v104
	v_mov_b32_e32 v125, v110
	v_mov_b32_e32 v110, v105
	v_mov_b32_e32 v104, v16
	s_waitcnt vmcnt(3)
	v_mov_b32_e32 v141, v40
	v_pk_fma_f32 v[106:107], v[124:125], v[140:141], v[106:107]
	s_waitcnt vmcnt(2)
	v_mov_b32_e32 v105, v44
	v_mov_b32_e32 v32, v29
	v_pk_mul_f32 v[24:25], v[108:109], v[36:37]
	v_pk_fma_f32 v[104:105], v[110:111], v[104:105], v[106:107]
	v_pk_fma_f32 v[24:25], v[122:123], v[32:33], v[24:25]
	v_mov_b32_e32 v40, v21
	v_add_f32_e32 v16, 0, v104
	v_pk_fma_f32 v[20:21], v[124:125], v[40:41], v[24:25]
	v_mov_b32_e32 v44, v17
	v_add_f32_e32 v107, v16, v105
	v_pk_fma_f32 v[16:17], v[110:111], v[44:45], v[20:21]
	v_mov_b32_e32 v20, v26
	v_add_f32_e32 v16, 0, v16
	v_mov_b32_e32 v21, v38
	v_add_f32_e32 v105, v16, v17
	v_mov_b32_e32 v16, v30
	v_mov_b32_e32 v17, v34
	v_pk_mul_f32 v[20:21], v[108:109], v[20:21]
	v_mov_b32_e32 v38, v27
	v_pk_fma_f32 v[16:17], v[122:123], v[16:17], v[20:21]
	v_mov_b32_e32 v20, v22
	v_mov_b32_e32 v21, v42
	v_pk_fma_f32 v[16:17], v[124:125], v[20:21], v[16:17]
	v_mov_b32_e32 v20, v18
	v_mov_b32_e32 v21, v46
	v_pk_fma_f32 v[16:17], v[110:111], v[20:21], v[16:17]
	v_mov_b32_e32 v34, v31
	v_add_f32_e32 v16, 0, v16
	v_add_f32_e32 v106, v16, v17
	v_pk_mul_f32 v[16:17], v[108:109], v[38:39]
	v_mov_b32_e32 v42, v23
	v_pk_fma_f32 v[16:17], v[122:123], v[34:35], v[16:17]
	v_mov_b32_e32 v46, v19
	v_pk_fma_f32 v[16:17], v[124:125], v[42:43], v[16:17]
	v_pk_mul_f32 v[20:21], v[102:103], v[98:99] op_sel_hi:[1,0]
	v_pk_fma_f32 v[16:17], v[110:111], v[46:47], v[16:17]
	s_waitcnt vmcnt(0)
	v_pk_fma_f32 v[50:51], v[20:21], v[50:51], v[54:55]
	v_add_f32_e32 v16, 0, v16
	v_add_f32_e32 v104, v16, v17
	v_pk_mul_f32 v[16:17], v[100:101], v[98:99] op_sel_hi:[1,0]
	v_cvt_pk_bf16_f32 v21, v50, v51
	v_pk_fma_f32 v[48:49], v[16:17], v[48:49], v[52:53]
	ds_read_b128 v[16:19], v60 offset:2048
	v_cvt_pk_bf16_f32 v20, v48, v49
	global_store_dwordx2 v[86:87], v[20:21], off
	ds_read_b128 v[20:23], v60 offset:6144
	v_pk_mul_f32 v[46:47], v[94:95], v[98:99] op_sel_hi:[1,0]
	s_waitcnt lgkmcnt(1)
	v_mul_f32_e32 v17, v49, v17
	v_fmac_f32_e32 v17, v48, v16
	v_fmac_f32_e32 v17, v50, v18
	v_fmac_f32_e32 v17, v51, v19
	v_add_f32_e32 v42, v126, v17
	ds_read_b128 v[16:19], v60 offset:10240
	s_waitcnt lgkmcnt(1)
	v_mul_f32_e32 v21, v49, v21
	v_fmac_f32_e32 v21, v48, v20
	v_fmac_f32_e32 v21, v50, v22
	v_fmac_f32_e32 v21, v51, v23
	v_add_f32_e32 v41, v127, v21
	ds_read_b128 v[20:23], v60 offset:14336
	s_waitcnt lgkmcnt(1)
	v_mul_f32_e32 v17, v49, v17
	v_fmac_f32_e32 v17, v48, v16
	v_fmac_f32_e32 v17, v50, v18
	v_fmac_f32_e32 v17, v51, v19
	v_add_f32_e32 v40, v129, v17
	ds_read_b128 v[16:19], v60 offset:18432
	global_load_dwordx4 v[32:35], v[66:67], off offset:3072
	global_load_dwordx4 v[36:39], v[68:69], off offset:3072
	s_waitcnt lgkmcnt(1)
	v_mul_f32_e32 v21, v49, v21
	v_fmac_f32_e32 v21, v48, v20
	v_fmac_f32_e32 v21, v50, v22
	v_fmac_f32_e32 v21, v51, v23
	v_add_f32_e32 v45, v130, v21
	ds_read_b128 v[20:23], v60 offset:22528
	s_waitcnt lgkmcnt(1)
	v_mul_f32_e32 v17, v49, v17
	v_fmac_f32_e32 v17, v48, v16
	v_fmac_f32_e32 v17, v50, v18
	v_fmac_f32_e32 v17, v51, v19
	v_add_f32_e32 v44, v132, v17
	ds_read_b128 v[16:19], v60 offset:26624
	s_waitcnt lgkmcnt(1)
	v_mul_f32_e32 v21, v49, v21
	v_fmac_f32_e32 v21, v48, v20
	v_fmac_f32_e32 v21, v50, v22
	v_fmac_f32_e32 v21, v51, v23
	v_add_f32_e32 v124, v133, v21
	ds_read_b128 v[20:23], v60 offset:30720
	s_waitcnt lgkmcnt(1)
	v_mul_f32_e32 v17, v49, v17
	v_fmac_f32_e32 v17, v48, v16
	v_fmac_f32_e32 v17, v50, v18
	v_fmac_f32_e32 v17, v51, v19
	s_waitcnt lgkmcnt(0)
	v_mul_f32_e32 v21, v49, v21
	v_fmac_f32_e32 v21, v48, v20
	v_fmac_f32_e32 v21, v50, v22
	v_add_f32_e32 v123, v134, v17
	ds_read_b128 v[16:19], v60 offset:34816
	v_fmac_f32_e32 v21, v51, v23
	v_add_f32_e32 v122, v135, v21
	ds_read_b128 v[20:23], v60 offset:38912
	s_waitcnt lgkmcnt(1)
	v_mul_f32_e32 v17, v49, v17
	v_fmac_f32_e32 v17, v48, v16
	v_fmac_f32_e32 v17, v50, v18
	s_waitcnt lgkmcnt(0)
	v_mul_f32_e32 v21, v49, v21
	v_fmac_f32_e32 v21, v48, v20
	v_fmac_f32_e32 v17, v51, v19
	v_fmac_f32_e32 v21, v50, v22
	v_add_f32_e32 v111, v136, v17
	ds_read_b128 v[16:19], v60 offset:43008
	v_fmac_f32_e32 v21, v51, v23
	v_add_f32_e32 v110, v137, v21
	ds_read_b128 v[20:23], v60 offset:47104
	s_waitcnt lgkmcnt(1)
	v_mul_f32_e32 v17, v49, v17
	v_fmac_f32_e32 v17, v48, v16
	v_fmac_f32_e32 v17, v50, v18
	s_waitcnt lgkmcnt(0)
	v_mul_f32_e32 v21, v49, v21
	v_fmac_f32_e32 v21, v48, v20
	v_fmac_f32_e32 v17, v51, v19
	v_fmac_f32_e32 v21, v50, v22
	v_add_f32_e32 v109, v138, v17
	ds_read_b128 v[16:19], v60 offset:51200
	v_fmac_f32_e32 v21, v51, v23
	v_add_f32_e32 v108, v131, v21
	ds_read_b128 v[20:23], v60 offset:55296
	s_waitcnt lgkmcnt(1)
	v_mul_f32_e32 v17, v49, v17
	v_fmac_f32_e32 v17, v48, v16
	v_fmac_f32_e32 v17, v50, v18
	s_waitcnt lgkmcnt(0)
	v_mul_f32_e32 v21, v49, v21
	v_fmac_f32_e32 v21, v48, v20
	v_fmac_f32_e32 v17, v51, v19
	v_fmac_f32_e32 v21, v50, v22
	v_add_f32_e32 v103, v139, v17
	ds_read_b128 v[16:19], v60 offset:59392
	v_fmac_f32_e32 v21, v51, v23
	v_add_f32_e32 v102, v148, v21
	ds_read_b128 v[20:23], v60 offset:63488
	s_waitcnt lgkmcnt(1)
	v_mul_f32_e32 v17, v49, v17
	v_fmac_f32_e32 v17, v48, v16
	v_fmac_f32_e32 v17, v50, v18
	s_waitcnt lgkmcnt(0)
	v_mul_f32_e32 v16, v49, v21
	v_fmac_f32_e32 v16, v48, v20
	v_fmac_f32_e32 v16, v50, v22
	v_fmac_f32_e32 v17, v51, v19
	v_fmac_f32_e32 v16, v51, v23
	v_add_f32_e32 v100, v144, v17
	v_add_f32_e32 v101, v142, v16
	global_load_dwordx4 v[16:19], v[76:77], off offset:48
	global_load_dwordx4 v[20:23], v[76:77], off offset:32
	global_load_dwordx4 v[24:27], v[76:77], off offset:16
	global_load_dwordx4 v[28:31], v[76:77], off
	s_waitcnt vmcnt(4)
	v_pk_fma_f32 v[52:53], v[46:47], v[32:33], v[36:37]
	v_pk_mul_f32 v[32:33], v[96:97], v[98:99] op_sel_hi:[1,0]
	ds_read_b128 v[94:97], v60 offset:3072
	v_pk_fma_f32 v[54:55], v[32:33], v[34:35], v[38:39]
	v_cvt_pk_bf16_f32 v32, v52, v53
	v_cvt_pk_bf16_f32 v33, v54, v55
	global_store_dwordx2 v[86:87], v[32:33], off offset:512
	ds_read_b128 v[32:35], v60 offset:7168
	s_waitcnt lgkmcnt(1)
	v_mul_f32_e32 v36, v53, v95
	v_fmac_f32_e32 v36, v52, v94
	v_fmac_f32_e32 v36, v54, v96
	v_fmac_f32_e32 v36, v55, v97
	v_add_f32_e32 v94, v42, v36
	ds_read_b128 v[36:39], v60 offset:11264
	ds_read_b128 v[130:133], v60 offset:15360
	s_waitcnt lgkmcnt(2)
	v_mul_f32_e32 v33, v53, v33
	v_fmac_f32_e32 v33, v52, v32
	v_fmac_f32_e32 v33, v54, v34
	s_waitcnt lgkmcnt(1)
	v_mul_f32_e32 v32, v53, v37
	v_fmac_f32_e32 v32, v52, v36
	v_fmac_f32_e32 v32, v54, v38
	v_fmac_f32_e32 v33, v55, v35
	v_fmac_f32_e32 v32, v55, v39
	v_add_f32_e32 v95, v41, v33
	v_add_f32_e32 v96, v40, v32
	ds_read_b128 v[40:43], v60 offset:19456
	s_waitcnt lgkmcnt(1)
	v_mul_f32_e32 v36, v53, v131
	v_fmac_f32_e32 v36, v52, v130
	v_fmac_f32_e32 v36, v54, v132
	v_fmac_f32_e32 v36, v55, v133
	v_add_f32_e32 v97, v45, v36
	ds_read_b128 v[130:133], v60 offset:23552
	s_waitcnt lgkmcnt(1)
	v_mul_f32_e32 v45, v53, v41
	global_load_dwordx4 v[32:35], v[78:79], off
	global_load_dwordx4 v[36:39], v[78:79], off offset:16
	v_fmac_f32_e32 v45, v52, v40
	v_fmac_f32_e32 v45, v54, v42
	v_fmac_f32_e32 v45, v55, v43
	global_load_dwordx4 v[40:43], v[78:79], off offset:32
	v_add_f32_e32 v125, v44, v45
	global_load_dwordx4 v[44:47], v[78:79], off offset:48
	ds_read_b128 v[134:137], v60 offset:27648
	s_waitcnt lgkmcnt(1)
	v_mul_f32_e32 v98, v53, v131
	v_fmac_f32_e32 v98, v52, v130
	v_fmac_f32_e32 v98, v54, v132
	v_fmac_f32_e32 v98, v55, v133
	ds_read_b128 v[130:133], v60 offset:31744
	v_add_f32_e32 v124, v124, v98
	s_waitcnt lgkmcnt(1)
	v_mul_f32_e32 v98, v53, v135
	v_fmac_f32_e32 v98, v52, v134
	v_fmac_f32_e32 v98, v54, v136
	v_fmac_f32_e32 v98, v55, v137
	ds_read_b128 v[134:137], v60 offset:35840
	v_add_f32_e32 v98, v123, v98
	s_waitcnt lgkmcnt(1)
	v_mul_f32_e32 v123, v53, v131
	v_fmac_f32_e32 v123, v52, v130
	v_fmac_f32_e32 v123, v54, v132
	v_fmac_f32_e32 v123, v55, v133
	ds_read_b128 v[130:133], v60 offset:39936
	v_add_f32_e32 v122, v122, v123
	s_waitcnt lgkmcnt(1)
	v_mul_f32_e32 v123, v53, v135
	v_fmac_f32_e32 v123, v52, v134
	v_fmac_f32_e32 v123, v54, v136
	v_fmac_f32_e32 v123, v55, v137
	ds_read_b128 v[134:137], v60 offset:44032
	v_add_f32_e32 v111, v111, v123
	s_waitcnt lgkmcnt(1)
	v_mul_f32_e32 v123, v53, v131
	v_fmac_f32_e32 v123, v52, v130
	v_fmac_f32_e32 v123, v54, v132
	v_fmac_f32_e32 v123, v55, v133
	ds_read_b128 v[130:133], v60 offset:48128
	v_add_f32_e32 v110, v110, v123
	s_waitcnt lgkmcnt(1)
	v_mul_f32_e32 v123, v53, v135
	v_fmac_f32_e32 v123, v52, v134
	v_fmac_f32_e32 v123, v54, v136
	v_fmac_f32_e32 v123, v55, v137
	ds_read_b128 v[134:137], v60 offset:52224
	v_add_f32_e32 v109, v109, v123
	s_waitcnt lgkmcnt(1)
	v_mul_f32_e32 v123, v53, v131
	v_fmac_f32_e32 v123, v52, v130
	v_fmac_f32_e32 v123, v54, v132
	v_fmac_f32_e32 v123, v55, v133
	ds_read_b128 v[130:133], v60 offset:56320
	v_add_f32_e32 v108, v108, v123
	s_waitcnt lgkmcnt(1)
	v_mul_f32_e32 v123, v53, v135
	v_fmac_f32_e32 v123, v52, v134
	v_fmac_f32_e32 v123, v54, v136
	v_fmac_f32_e32 v123, v55, v137
	ds_read_b128 v[134:137], v60 offset:60416
	v_add_f32_e32 v103, v103, v123
	s_waitcnt lgkmcnt(1)
	v_mul_f32_e32 v123, v53, v131
	v_fmac_f32_e32 v123, v52, v130
	v_fmac_f32_e32 v123, v54, v132
	v_fmac_f32_e32 v123, v55, v133
	ds_read_b128 v[130:133], v60 offset:64512
	v_add_f32_e32 v102, v102, v123
	s_waitcnt lgkmcnt(1)
	v_mul_f32_e32 v123, v53, v135
	v_fmac_f32_e32 v123, v52, v134
	v_fmac_f32_e32 v123, v54, v136
	v_fmac_f32_e32 v123, v55, v137
	v_add_f32_e32 v123, v100, v123
	s_waitcnt lgkmcnt(0)
	v_mul_f32_e32 v100, v53, v131
	v_fmac_f32_e32 v100, v52, v130
	v_fmac_f32_e32 v100, v54, v132
	v_fmac_f32_e32 v100, v55, v133
	v_add_f32_e32 v129, v101, v100
	v_mov_b32_e32 v100, v48
	v_mov_b32_e32 v101, v52
	v_mov_b32_e32 v52, v49
	s_waitcnt vmcnt(6)
	v_mov_b32_e32 v48, v24
	s_waitcnt vmcnt(5)
	v_mov_b32_e32 v126, v28
	v_mov_b32_e32 v130, v20
	s_waitcnt vmcnt(3)
	v_mov_b32_e32 v127, v32
	s_waitcnt vmcnt(2)
	v_mov_b32_e32 v49, v36
	v_pk_mul_f32 v[48:49], v[52:53], v[48:49]
	v_mov_b32_e32 v36, v25
	v_pk_fma_f32 v[48:49], v[100:101], v[126:127], v[48:49]
	v_mov_b32_e32 v126, v50
	v_mov_b32_e32 v127, v54
	s_waitcnt vmcnt(1)
	v_mov_b32_e32 v131, v40
	v_pk_fma_f32 v[48:49], v[126:127], v[130:131], v[48:49]
	v_mov_b32_e32 v54, v51
	v_mov_b32_e32 v50, v16
	s_waitcnt vmcnt(0)
	v_mov_b32_e32 v0, s23
	v_min_u32_e32 v0, 15, v0
	v_mov_b32_e32 v1, 0
	v_lshl_add_u64 v[0:1], v[82:83], 0, v[0:1]
	v_lshlrev_b64 v[2:3], 12, v[0:1]
	v_lshlrev_b64 v[0:1], 11, v[0:1]
	v_lshl_add_u64 v[12:13], v[62:63], 0, v[2:3]
	v_lshl_add_u64 v[92:93], v[64:65], 0, v[0:1]
	global_load_dwordx4 v[0:3], v[12:13], off
	global_load_dwordx2 v[84:85], v[92:93], off
	global_load_dwordx4 v[4:7], v[12:13], off offset:1024
	global_load_dwordx2 v[88:89], v[92:93], off offset:512
	global_load_dwordx4 v[8:11], v[12:13], off offset:2048
	global_load_dwordx2 v[90:91], v[92:93], off offset:1024
	s_nop 0
	global_load_dwordx4 v[12:15], v[12:13], off offset:3072
	s_nop 0
	global_load_dwordx2 v[92:93], v[92:93], off offset:1536
	v_mov_b32_e32 v51, v44
	v_mov_b32_e32 v32, v29
	v_pk_mul_f32 v[24:25], v[52:53], v[36:37]
	v_pk_fma_f32 v[48:49], v[54:55], v[50:51], v[48:49]
	v_pk_fma_f32 v[24:25], v[100:101], v[32:33], v[24:25]
	v_mov_b32_e32 v40, v21
	v_add_f32_e32 v16, v107, v48
	v_pk_fma_f32 v[20:21], v[126:127], v[40:41], v[24:25]
	v_mov_b32_e32 v44, v17
	v_add_f32_e32 v28, v16, v49
	v_pk_fma_f32 v[16:17], v[54:55], v[44:45], v[20:21]
	v_mov_b32_e32 v20, v26
	v_add_f32_e32 v16, v105, v16
	v_mov_b32_e32 v21, v38
	v_add_f32_e32 v24, v16, v17
	v_mov_b32_e32 v16, v30
	v_mov_b32_e32 v17, v34
	v_pk_mul_f32 v[20:21], v[52:53], v[20:21]
	v_mov_b32_e32 v38, v27
	v_pk_fma_f32 v[16:17], v[100:101], v[16:17], v[20:21]
	v_mov_b32_e32 v20, v22
	v_mov_b32_e32 v21, v42
	v_pk_fma_f32 v[16:17], v[126:127], v[20:21], v[16:17]
	v_mov_b32_e32 v20, v18
	v_mov_b32_e32 v21, v46
	v_pk_fma_f32 v[16:17], v[54:55], v[20:21], v[16:17]
	v_mov_b32_e32 v34, v31
	v_add_f32_e32 v16, v106, v16
	v_add_f32_e32 v20, v16, v17
	v_pk_mul_f32 v[16:17], v[52:53], v[38:39]
	v_mov_b32_e32 v42, v23
	v_pk_fma_f32 v[16:17], v[100:101], v[34:35], v[16:17]
	v_mov_b32_e32 v46, v19
	v_pk_fma_f32 v[16:17], v[126:127], v[42:43], v[16:17]
	v_add_f32_dpp v18, v24, v24 quad_perm:[1,0,3,2] row_mask:0xf bank_mask:0xf bound_ctrl:1
	v_pk_fma_f32 v[16:17], v[54:55], v[46:47], v[16:17]
	v_add_f32_dpp v20, v20, v20 quad_perm:[1,0,3,2] row_mask:0xf bank_mask:0xf bound_ctrl:1
	v_add_f32_e32 v16, v104, v16
	v_add_f32_e32 v22, v16, v17
	v_add_f32_dpp v18, v18, v18 quad_perm:[2,3,0,1] row_mask:0xf bank_mask:0xf bound_ctrl:1
	v_add_f32_dpp v16, v28, v28 quad_perm:[1,0,3,2] row_mask:0xf bank_mask:0xf bound_ctrl:1
	v_add_f32_dpp v20, v20, v20 quad_perm:[2,3,0,1] row_mask:0xf bank_mask:0xf bound_ctrl:1
	v_add_f32_dpp v18, v18, v18 row_half_mirror row_mask:0xf bank_mask:0xf bound_ctrl:1
	v_add_f32_dpp v16, v16, v16 quad_perm:[2,3,0,1] row_mask:0xf bank_mask:0xf bound_ctrl:1
	v_add_f32_dpp v20, v20, v20 row_half_mirror row_mask:0xf bank_mask:0xf bound_ctrl:1
	v_add_f32_dpp v18, v18, v18 row_mirror row_mask:0xf bank_mask:0xf bound_ctrl:1
	v_add_f32_dpp v16, v16, v16 row_half_mirror row_mask:0xf bank_mask:0xf bound_ctrl:1
	v_add_f32_dpp v20, v20, v20 row_mirror row_mask:0xf bank_mask:0xf bound_ctrl:1
	s_nop 0
	v_add_f32_dpp v16, v16, v16 row_mirror row_mask:0xf bank_mask:0xf bound_ctrl:1
	s_nop 0
	v_readlane_b32 s2, v16, 16
	v_readlane_b32 s4, v16, 48
	v_readlane_b32 s0, v16, 0
	v_readlane_b32 s1, v16, 32
	v_mov_b32_e32 v16, s2
	v_mov_b32_e32 v17, s4
	v_readlane_b32 s2, v18, 16
	v_readlane_b32 s4, v18, 48
	v_pk_add_f32 v[16:17], s[0:1], v[16:17]
	v_readlane_b32 s0, v18, 0
	v_readlane_b32 s1, v18, 32
	v_mov_b32_e32 v18, s2
	v_mov_b32_e32 v19, s4
	v_readlane_b32 s2, v20, 16
	v_readlane_b32 s4, v20, 48
	v_pk_add_f32 v[18:19], s[0:1], v[18:19]
	v_readlane_b32 s0, v20, 0
	v_readlane_b32 s1, v20, 32
	v_mov_b32_e32 v20, s2
	v_mov_b32_e32 v21, s4
	v_pk_add_f32 v[20:21], s[0:1], v[20:21]
	v_mov_b32_e32 v25, v18
	v_add_f32_e32 v26, v20, v21
	v_add_f32_dpp v20, v22, v22 quad_perm:[1,0,3,2] row_mask:0xf bank_mask:0xf bound_ctrl:1
	v_mov_b32_e32 v18, v17
	s_nop 0
	v_add_f32_dpp v20, v20, v20 quad_perm:[2,3,0,1] row_mask:0xf bank_mask:0xf bound_ctrl:1
	s_nop 1
	v_add_f32_dpp v20, v20, v20 row_half_mirror row_mask:0xf bank_mask:0xf bound_ctrl:1
	s_nop 1
	v_add_f32_dpp v20, v20, v20 row_mirror row_mask:0xf bank_mask:0xf bound_ctrl:1
	s_nop 0
	v_readlane_b32 s2, v20, 16
	v_readlane_b32 s4, v20, 48
	v_readlane_b32 s0, v20, 0
	v_readlane_b32 s1, v20, 32
	v_mov_b32_e32 v20, s2
	v_mov_b32_e32 v21, s4
	v_pk_add_f32 v[20:21], s[0:1], v[20:21]
	s_nop 0
	v_add_f32_e32 v27, v20, v21
	v_add_f32_dpp v20, v94, v94 quad_perm:[1,0,3,2] row_mask:0xf bank_mask:0xf bound_ctrl:1
	s_nop 1
	v_add_f32_dpp v20, v20, v20 quad_perm:[2,3,0,1] row_mask:0xf bank_mask:0xf bound_ctrl:1
	s_nop 1
	v_add_f32_dpp v20, v20, v20 row_half_mirror row_mask:0xf bank_mask:0xf bound_ctrl:1
	s_nop 1
	v_add_f32_dpp v20, v20, v20 row_mirror row_mask:0xf bank_mask:0xf bound_ctrl:1
	s_nop 0
	v_readlane_b32 s20, v20, 0
	v_readlane_b32 s4, v20, 16
	v_readlane_b32 s21, v20, 32
	v_readlane_b32 s5, v20, 48
	v_add_f32_dpp v20, v95, v95 quad_perm:[1,0,3,2] row_mask:0xf bank_mask:0xf bound_ctrl:1
	s_nop 1
	v_add_f32_dpp v20, v20, v20 quad_perm:[2,3,0,1] row_mask:0xf bank_mask:0xf bound_ctrl:1
	s_nop 1
	v_add_f32_dpp v20, v20, v20 row_half_mirror row_mask:0xf bank_mask:0xf bound_ctrl:1
	s_nop 1
	v_add_f32_dpp v20, v20, v20 row_mirror row_mask:0xf bank_mask:0xf bound_ctrl:1
	s_nop 0
	v_readlane_b32 s91, v20, 0
	v_readlane_b32 s95, v20, 16
	v_readlane_b32 s94, v20, 32
	v_readlane_b32 s92, v20, 48
	v_add_f32_dpp v20, v96, v96 quad_perm:[1,0,3,2] row_mask:0xf bank_mask:0xf bound_ctrl:1
	s_nop 1
	v_add_f32_dpp v20, v20, v20 quad_perm:[2,3,0,1] row_mask:0xf bank_mask:0xf bound_ctrl:1
	s_nop 1
	v_add_f32_dpp v20, v20, v20 row_half_mirror row_mask:0xf bank_mask:0xf bound_ctrl:1
	s_nop 1
	v_add_f32_dpp v20, v20, v20 row_mirror row_mask:0xf bank_mask:0xf bound_ctrl:1
	s_nop 0
	v_readlane_b32 s6, v20, 0
	v_readlane_b32 s75, v20, 16
	v_readlane_b32 s74, v20, 32
	v_readlane_b32 s84, v20, 48
	v_add_f32_dpp v20, v97, v97 quad_perm:[1,0,3,2] row_mask:0xf bank_mask:0xf bound_ctrl:1
	s_nop 1
	v_add_f32_dpp v20, v20, v20 quad_perm:[2,3,0,1] row_mask:0xf bank_mask:0xf bound_ctrl:1
	s_nop 1
	v_add_f32_dpp v20, v20, v20 row_half_mirror row_mask:0xf bank_mask:0xf bound_ctrl:1
	s_nop 1
	v_add_f32_dpp v20, v20, v20 row_mirror row_mask:0xf bank_mask:0xf bound_ctrl:1
	s_nop 0
	v_readlane_b32 s97, v20, 0
	v_readlane_b32 s9, v20, 16
	v_readlane_b32 s8, v20, 32
	v_readlane_b32 s12, v20, 48
	v_add_f32_dpp v20, v125, v125 quad_perm:[1,0,3,2] row_mask:0xf bank_mask:0xf bound_ctrl:1
	s_nop 1
	v_add_f32_dpp v20, v20, v20 quad_perm:[2,3,0,1] row_mask:0xf bank_mask:0xf bound_ctrl:1
	s_nop 1
	v_add_f32_dpp v20, v20, v20 row_half_mirror row_mask:0xf bank_mask:0xf bound_ctrl:1
	s_nop 1
	v_add_f32_dpp v20, v20, v20 row_mirror row_mask:0xf bank_mask:0xf bound_ctrl:1
	s_nop 0
	v_readlane_b32 s59, v20, 0
	v_readlane_b32 s61, v20, 16
	v_readlane_b32 s60, v20, 32
	v_readlane_b32 s82, v20, 48
	v_add_f32_dpp v20, v124, v124 quad_perm:[1,0,3,2] row_mask:0xf bank_mask:0xf bound_ctrl:1
	s_nop 1
	v_add_f32_dpp v20, v20, v20 quad_perm:[2,3,0,1] row_mask:0xf bank_mask:0xf bound_ctrl:1
	s_nop 1
	v_add_f32_dpp v20, v20, v20 row_half_mirror row_mask:0xf bank_mask:0xf bound_ctrl:1
	s_nop 1
	v_add_f32_dpp v24, v20, v20 row_mirror row_mask:0xf bank_mask:0xf bound_ctrl:1
	s_nop 0
	v_readlane_b32 s52, v24, 0
	v_readlane_b32 s54, v24, 16
	v_readlane_b32 s53, v24, 32
	v_readlane_b32 s93, v24, 48
	v_add_f32_dpp v24, v98, v98 quad_perm:[1,0,3,2] row_mask:0xf bank_mask:0xf bound_ctrl:1
	s_nop 1
	v_add_f32_dpp v24, v24, v24 quad_perm:[2,3,0,1] row_mask:0xf bank_mask:0xf bound_ctrl:1
	s_nop 1
	v_add_f32_dpp v24, v24, v24 row_half_mirror row_mask:0xf bank_mask:0xf bound_ctrl:1
	s_nop 1
	v_add_f32_dpp v24, v24, v24 row_mirror row_mask:0xf bank_mask:0xf bound_ctrl:1
	s_nop 0
	v_readlane_b32 s85, v24, 0
	v_readlane_b32 s87, v24, 16
	v_readlane_b32 s86, v24, 32
	v_readlane_b32 s90, v24, 48
	v_add_f32_dpp v24, v122, v122 quad_perm:[1,0,3,2] row_mask:0xf bank_mask:0xf bound_ctrl:1
	s_nop 1
	v_add_f32_dpp v24, v24, v24 quad_perm:[2,3,0,1] row_mask:0xf bank_mask:0xf bound_ctrl:1
	s_nop 1
	v_add_f32_dpp v24, v24, v24 row_half_mirror row_mask:0xf bank_mask:0xf bound_ctrl:1
	s_nop 1
	v_add_f32_dpp v24, v24, v24 row_mirror row_mask:0xf bank_mask:0xf bound_ctrl:1
	s_nop 0
	v_readlane_b32 s13, v24, 0
	v_readlane_b32 s24, v24, 16
	v_readlane_b32 s16, v24, 32
	v_readlane_b32 s17, v24, 48
	v_add_f32_dpp v24, v111, v111 quad_perm:[1,0,3,2] row_mask:0xf bank_mask:0xf bound_ctrl:1
	s_nop 1
	v_add_f32_dpp v24, v24, v24 quad_perm:[2,3,0,1] row_mask:0xf bank_mask:0xf bound_ctrl:1
	s_nop 1
	v_add_f32_dpp v24, v24, v24 row_half_mirror row_mask:0xf bank_mask:0xf bound_ctrl:1
	s_nop 1
	v_add_f32_dpp v24, v24, v24 row_mirror row_mask:0xf bank_mask:0xf bound_ctrl:1
	s_nop 0
	v_readlane_b32 s83, v24, 0
	v_readlane_b32 s89, v24, 16
	v_readlane_b32 s88, v24, 32
	v_readlane_b32 s96, v24, 48
	v_add_f32_dpp v24, v110, v110 quad_perm:[1,0,3,2] row_mask:0xf bank_mask:0xf bound_ctrl:1
	s_nop 1
	v_add_f32_dpp v24, v24, v24 quad_perm:[2,3,0,1] row_mask:0xf bank_mask:0xf bound_ctrl:1
	s_nop 1
	v_add_f32_dpp v24, v24, v24 row_half_mirror row_mask:0xf bank_mask:0xf bound_ctrl:1
	s_nop 1
	v_add_f32_dpp v24, v24, v24 row_mirror row_mask:0xf bank_mask:0xf bound_ctrl:1
	s_nop 0
	v_readlane_b32 s55, v24, 0
	v_readlane_b32 s57, v24, 16
	v_readlane_b32 s56, v24, 32
	v_readlane_b32 s58, v24, 48
	v_add_f32_dpp v24, v109, v109 quad_perm:[1,0,3,2] row_mask:0xf bank_mask:0xf bound_ctrl:1
	s_nop 1
	v_add_f32_dpp v24, v24, v24 quad_perm:[2,3,0,1] row_mask:0xf bank_mask:0xf bound_ctrl:1
	s_nop 1
	v_add_f32_dpp v24, v24, v24 row_half_mirror row_mask:0xf bank_mask:0xf bound_ctrl:1
	s_nop 1
	v_add_f32_dpp v24, v24, v24 row_mirror row_mask:0xf bank_mask:0xf bound_ctrl:1
	s_nop 0
	v_readlane_b32 s46, v24, 0
	v_readlane_b32 s48, v24, 16
	v_readlane_b32 s47, v24, 32
	v_readlane_b32 s49, v24, 48
	v_add_f32_dpp v24, v108, v108 quad_perm:[1,0,3,2] row_mask:0xf bank_mask:0xf bound_ctrl:1
	s_nop 1
	v_add_f32_dpp v24, v24, v24 quad_perm:[2,3,0,1] row_mask:0xf bank_mask:0xf bound_ctrl:1
	s_nop 1
	v_add_f32_dpp v24, v24, v24 row_half_mirror row_mask:0xf bank_mask:0xf bound_ctrl:1
	s_nop 1
	v_add_f32_dpp v24, v24, v24 row_mirror row_mask:0xf bank_mask:0xf bound_ctrl:1
	s_nop 0
	v_readlane_b32 s38, v24, 0
	v_readlane_b32 s40, v24, 16
	v_readlane_b32 s39, v24, 32
	v_readlane_b32 s41, v24, 48
	v_add_f32_dpp v24, v103, v103 quad_perm:[1,0,3,2] row_mask:0xf bank_mask:0xf bound_ctrl:1
	s_nop 1
	v_add_f32_dpp v24, v24, v24 quad_perm:[2,3,0,1] row_mask:0xf bank_mask:0xf bound_ctrl:1
	s_nop 1
	v_add_f32_dpp v24, v24, v24 row_half_mirror row_mask:0xf bank_mask:0xf bound_ctrl:1
	s_nop 1
	v_add_f32_dpp v24, v24, v24 row_mirror row_mask:0xf bank_mask:0xf bound_ctrl:1
	s_nop 0
	v_readlane_b32 s34, v24, 0
	v_readlane_b32 s36, v24, 16
	v_readlane_b32 s35, v24, 32
	v_readlane_b32 s37, v24, 48
	v_add_f32_dpp v24, v102, v102 quad_perm:[1,0,3,2] row_mask:0xf bank_mask:0xf bound_ctrl:1
	s_nop 1
	v_add_f32_dpp v24, v24, v24 quad_perm:[2,3,0,1] row_mask:0xf bank_mask:0xf bound_ctrl:1
	s_nop 1
	v_add_f32_dpp v24, v24, v24 row_half_mirror row_mask:0xf bank_mask:0xf bound_ctrl:1
	s_nop 1
	v_add_f32_dpp v24, v24, v24 row_mirror row_mask:0xf bank_mask:0xf bound_ctrl:1
	s_nop 0
	v_readlane_b32 s29, v24, 0
	v_readlane_b32 s31, v24, 16
	v_readlane_b32 s30, v24, 32
	v_readlane_b32 s33, v24, 48
	v_add_f32_dpp v24, v123, v123 quad_perm:[1,0,3,2] row_mask:0xf bank_mask:0xf bound_ctrl:1
	s_nop 1
	v_add_f32_dpp v24, v24, v24 quad_perm:[2,3,0,1] row_mask:0xf bank_mask:0xf bound_ctrl:1
	s_nop 1
	v_add_f32_dpp v24, v24, v24 row_half_mirror row_mask:0xf bank_mask:0xf bound_ctrl:1
	s_nop 1
	v_add_f32_dpp v28, v24, v24 row_mirror row_mask:0xf bank_mask:0xf bound_ctrl:1
	v_add_f32_dpp v24, v129, v129 quad_perm:[1,0,3,2] row_mask:0xf bank_mask:0xf bound_ctrl:1
	v_readlane_b32 s25, v28, 0
	v_readlane_b32 s28, v28, 16
	v_add_f32_dpp v24, v24, v24 quad_perm:[2,3,0,1] row_mask:0xf bank_mask:0xf bound_ctrl:1
	v_readlane_b32 s50, v28, 32
	v_readlane_b32 s51, v28, 48
	v_add_f32_dpp v24, v24, v24 row_half_mirror row_mask:0xf bank_mask:0xf bound_ctrl:1
	s_nop 1
	v_add_f32_dpp v29, v24, v24 row_mirror row_mask:0xf bank_mask:0xf bound_ctrl:1
	v_mov_b32_e32 v24, v16
	v_pk_add_f32 v[16:17], v[24:25], v[18:19]
	v_mov_b32_e32 v20, v178
	v_mov_b32_e32 v21, v179
	v_mov_b32_e32 v22, v180
	v_mov_b32_e32 v23, v181
	v_add_f32_e32 v19, v26, v22
	v_pk_add_f32 v[16:17], v[16:17], v[20:21]
	v_add_f32_e32 v18, v27, v23
	v_cmp_gt_f32_e32 vcc, v17, v16
	v_mov_b32_e32 v22, 0
	v_readlane_b32 s42, v29, 0
	v_cndmask_b32_e32 v20, v16, v17, vcc
	v_cmp_gt_f32_e64 s[18:19], v19, v20
	v_cndmask_b32_e64 v21, 0, 1, vcc
	s_and_b64 s[14:15], s[18:19], exec
	v_cndmask_b32_e64 v20, v20, v19, s[18:19]
	v_cmp_ngt_f32_e64 s[0:1], v18, v20
	v_readfirstlane_b32 s2, v21
	s_cselect_b32 s2, 2, s2
	s_and_b64 s[14:15], s[0:1], exec
	s_cselect_b32 s2, s2, 3
	s_cmp_eq_u32 s2, 0
	s_cselect_b64 s[26:27], -1, 0
	s_cmp_lg_u32 s2, 0
	v_mov_b32_e32 v21, 0
	v_readlane_b32 s44, v29, 16
	v_readlane_b32 s43, v29, 32
	v_readlane_b32 s45, v29, 48
	v_cmp_gt_f32_e64 s[14:15], v18, v20
	s_cbranch_scc0 .LBB0_560
	v_cndmask_b32_e64 v23, 0, 1, s[26:27]
	v_cmp_ne_u32_e64 s[20:21], 1, v23
	s_andn2_b64 vcc, exec, s[26:27]
	s_cbranch_vccz .LBB0_561

.LBB0_557:
	v_mov_b32_e32 v22, s61
	v_mov_b32_e32 v25, s82
	v_add_f32_e32 v22, s59, v22
	v_add_f32_e32 v25, s60, v25
	v_add_f32_e32 v22, v22, v25
	v_mov_b32_e32 v25, v166
	v_add_f32_e32 v22, v22, v25
	v_cndmask_b32_e64 v25, 0, 1, s[26:27]
	v_cmp_ne_u32_e64 s[20:21], 1, v25
	s_andn2_b64 vcc, exec, s[26:27]
	s_cbranch_vccz .LBB0_565

.LBB0_559:
	v_mov_b32_e32 v24, s87
	v_mov_b32_e32 v25, s90
	v_add_f32_e32 v24, s85, v24
	v_add_f32_e32 v25, s86, v25
	v_add_f32_e32 v24, v24, v25
	v_mov_b32_e32 v25, v168
	v_add_f32_e32 v24, v24, v25
	s_and_b64 vcc, exec, s[20:21]
	s_cbranch_vccz .LBB0_567
	s_branch .LBB0_568
.LBB0_560:
	v_mov_b32_e32 v22, s4
	v_mov_b32_e32 v23, s5
	v_pk_add_f32 v[22:23], s[20:21], v[22:23]
	s_nop 0
	v_add_f32_e32 v22, v22, v23
	v_mov_b32_e32 v23, v162
	v_add_f32_e32 v22, v22, v23
	v_cndmask_b32_e64 v23, 0, 1, s[26:27]
	v_cmp_ne_u32_e64 s[20:21], 1, v23
	s_andn2_b64 vcc, exec, s[26:27]
	s_cbranch_vccnz .LBB0_554
.LBB0_561:
	v_mov_b32_e32 v21, s95
	v_mov_b32_e32 v23, s92
	v_add_f32_e32 v21, s91, v21
	v_add_f32_e32 v23, s94, v23
	v_add_f32_e32 v21, v21, v23
	v_mov_b32_e32 v23, v163
	v_add_f32_e32 v21, v21, v23
	v_mov_b32_e32 v23, 0
	s_and_b64 vcc, exec, s[20:21]
	v_mov_b32_e32 v24, 0
	s_cbranch_vccnz .LBB0_555
.LBB0_562:
	v_mov_b32_e32 v24, s75
	v_mov_b32_e32 v25, s84
	v_add_f32_e32 v24, s6, v24
	v_add_f32_e32 v25, s74, v25
	v_add_f32_e32 v24, v24, v25
	v_mov_b32_e32 v25, v164
	v_add_f32_e32 v24, v24, v25
	s_and_b64 vcc, exec, s[20:21]
	s_cbranch_vccnz .LBB0_556
.LBB0_563:
	v_mov_b32_e32 v23, s9
	v_mov_b32_e32 v25, s12
	v_add_f32_e32 v23, s97, v23
	v_add_f32_e32 v25, s8, v25
	v_add_f32_e32 v23, v23, v25
	v_mov_b32_e32 v25, v165
	v_add_f32_e32 v23, v23, v25
	s_cmp_eq_u32 s2, 1
	s_cselect_b64 s[26:27], -1, 0
	s_cmp_lg_u32 s2, 1
	s_cbranch_scc0 .LBB0_557

.LBB0_565:
	v_mov_b32_e32 v21, s54
	v_mov_b32_e32 v25, s93
	v_add_f32_e32 v21, s52, v21
	v_add_f32_e32 v25, s53, v25
	v_add_f32_e32 v21, v21, v25
	v_mov_b32_e32 v25, v167
	v_add_f32_e32 v21, v21, v25
	s_and_b64 vcc, exec, s[20:21]
	s_cbranch_vccz .LBB0_559

.LBB0_567:
	v_mov_b32_e32 v23, s24
	v_mov_b32_e32 v25, s17
	v_add_f32_e32 v23, s13, v23
	v_add_f32_e32 v25, s16, v25
	v_add_f32_e32 v23, v23, v25
	v_mov_b32_e32 v25, v169
	v_add_f32_e32 v23, v23, v25
.LBB0_568:
	s_and_b64 s[4:5], s[18:19], s[0:1]
	v_cndmask_b32_e64 v25, 0, 1, s[4:5]
	v_cmp_ne_u32_e64 s[18:19], 1, v25
	s_andn2_b64 vcc, exec, s[4:5]
	s_cbranch_vccnz .LBB0_570
	v_mov_b32_e32 v22, s89
	v_mov_b32_e32 v25, s96
	v_add_f32_e32 v22, s83, v22
	v_add_f32_e32 v25, s88, v25
	v_add_f32_e32 v22, v22, v25
	v_mov_b32_e32 v25, v170
	v_add_f32_e32 v22, v22, v25
.LBB0_570:
	s_and_b64 vcc, exec, s[18:19]
	s_cbranch_vccnz .LBB0_572
	v_mov_b32_e32 v21, s57
	v_mov_b32_e32 v25, s58
	v_add_f32_e32 v21, s55, v21
	v_add_f32_e32 v25, s56, v25
	v_add_f32_e32 v21, v21, v25
	v_mov_b32_e32 v25, v171
	v_add_f32_e32 v21, v21, v25
.LBB0_572:
	v_readlane_b32 s88, v237, 56
	s_and_b64 vcc, exec, s[18:19]
	v_readlane_b32 s52, v237, 48
	v_readlane_b32 s89, v237, 57
	v_readlane_b32 s90, v237, 58
	v_readlane_b32 s91, v237, 59
	v_readlane_b32 s53, v237, 49
	v_readlane_b32 s54, v237, 50
	v_readlane_b32 s55, v237, 51
	v_readlane_b32 s56, v237, 52
	v_readlane_b32 s57, v237, 53
	v_readlane_b32 s58, v237, 54
	v_readlane_b32 s59, v237, 55
	s_cbranch_vccnz .LBB0_579
	v_mov_b32_e32 v24, s48
	v_mov_b32_e32 v25, s49
	v_add_f32_e32 v24, s46, v24
	v_add_f32_e32 v25, s47, v25
	v_add_f32_e32 v24, v24, v25
	v_mov_b32_e32 v25, v172
	v_add_f32_e32 v24, v24, v25
	s_and_b64 vcc, exec, s[18:19]
	s_cbranch_vccz .LBB0_580

.LBB0_575:
	v_mov_b32_e32 v22, v174
	v_mov_b32_e32 v25, s36
	v_mov_b32_e32 v26, s37
	v_add_f32_e32 v25, s34, v25
	v_add_f32_e32 v26, s35, v26
	v_add_f32_e32 v25, v25, v26
	v_add_f32_e32 v22, v25, v22
	s_and_b64 vcc, exec, s[18:19]
	s_cbranch_vccz .LBB0_582

.LBB0_577:
	v_mov_b32_e32 v24, v176
	v_mov_b32_e32 v25, s28
	v_mov_b32_e32 v26, s51
	v_add_f32_e32 v25, s25, v25
	v_add_f32_e32 v26, s50, v26
	v_add_f32_e32 v25, v25, v26
	v_add_f32_e32 v24, v25, v24
	s_and_b64 vcc, exec, s[18:19]
	s_cbranch_vccz .LBB0_584

.LBB0_580:
	v_mov_b32_e32 v23, s40
	v_mov_b32_e32 v25, s41
	v_add_f32_e32 v23, s38, v23
	v_add_f32_e32 v25, s39, v25
	v_add_f32_e32 v23, v23, v25
	v_mov_b32_e32 v25, v173
	v_add_f32_e32 v23, v23, v25
	v_cndmask_b32_e64 v25, 0, 1, s[14:15]
	v_cmp_ne_u32_e64 s[18:19], 1, v25
	s_andn2_b64 vcc, exec, s[14:15]
	s_cbranch_vccz .LBB0_575

.LBB0_582:
	v_mov_b32_e32 v21, v175
	v_mov_b32_e32 v25, s31
	v_mov_b32_e32 v26, s33
	v_add_f32_e32 v25, s29, v25
	v_add_f32_e32 v26, s30, v26
	v_add_f32_e32 v25, v25, v26
	v_add_f32_e32 v21, v25, v21
	s_and_b64 vcc, exec, s[18:19]
	s_cbranch_vccz .LBB0_577

.LBB0_584:
	v_mov_b32_e32 v23, v177
	v_mov_b32_e32 v25, s44
	v_mov_b32_e32 v26, s45
	v_add_f32_e32 v25, s42, v25
	v_add_f32_e32 v26, s43, v26
	v_add_f32_e32 v25, v25, v26
	v_add_f32_e32 v23, v25, v23
	s_and_saveexec_b64 s[26:27], s[10:11]
	s_cbranch_execz .LBB0_551

.LBB0_1672:
	s_barrier
	s_and_saveexec_b64 s[0:1], s[4:5]
	ds_write_b32 v99, v61
	s_or_b64 exec, exec, s[0:1]
	s_lshl_b32 s22, s17, 6
	s_ashr_i32 s23, s22, 31
	v_lshl_add_u64 v[82:83], s[22:23], 0, v[58:59]
	v_lshlrev_b64 v[0:1], 12, v[82:83]
	v_lshl_add_u64 v[0:1], v[62:63], 0, v[0:1]
	v_lshlrev_b64 v[2:3], 11, v[82:83]
	v_lshl_add_u64 v[2:3], v[64:65], 0, v[2:3]
	global_load_dwordx4 v[28:31], v[0:1], off
	global_load_dwordx4 v[20:23], v[0:1], off offset:1024
	global_load_dwordx4 v[24:27], v[0:1], off offset:2048
	global_load_dwordx4 v[16:19], v[0:1], off offset:3072
	global_load_dwordx2 v[84:85], v[2:3], off
	global_load_dwordx2 v[88:89], v[2:3], off offset:512
	global_load_dwordx2 v[90:91], v[2:3], off offset:1024
	global_load_dwordx2 v[92:93], v[2:3], off offset:1536
	global_load_dword v162, v61, s[72:73] offset:64
	global_load_dword v163, v61, s[72:73] offset:68
	global_load_dword v164, v61, s[72:73] offset:72
	global_load_dword v165, v61, s[72:73] offset:76
	global_load_dword v166, v61, s[72:73] offset:80
	global_load_dword v167, v61, s[72:73] offset:84
	global_load_dword v168, v61, s[72:73] offset:88
	global_load_dword v169, v61, s[72:73] offset:92
	global_load_dword v170, v61, s[72:73] offset:96
	global_load_dword v171, v61, s[72:73] offset:100
	global_load_dword v172, v61, s[72:73] offset:104
	global_load_dword v173, v61, s[72:73] offset:108
	global_load_dword v174, v61, s[72:73] offset:112
	global_load_dword v175, v61, s[72:73] offset:116
	global_load_dword v176, v61, s[72:73] offset:120
	global_load_dword v177, v61, s[72:73] offset:124
	global_load_dwordx4 v[178:181], v61, s[68:69] offset:16
	s_ashr_i32 s19, s18, 31
	v_lshl_add_u64 v[0:1], v[58:59], 0, s[18:19]
	v_lshlrev_b64 v[0:1], 11, v[0:1]
	v_lshl_add_u64 v[86:87], v[80:81], 0, v[0:1]
	s_mov_b32 s19, 0
	v_mov_b32_e32 v121, v115
	s_branch .LBB0_1676
.LBB0_1675:
	s_or_b64 exec, exec, s[24:25]
	s_mov_b64 s[0:1], 0x800
	v_add_u32_e32 v121, 4, v121
	v_lshl_add_u64 v[86:87], v[86:87], 0, s[0:1]
	s_cmp_eq_u32 s21, 16
	s_mov_b32 s19, s21
	s_waitcnt vmcnt(0)
	v_mov_b64_e32 v[28:29], v[0:1]
	v_mov_b64_e32 v[30:31], v[2:3]
	v_mov_b64_e32 v[20:21], v[4:5]
	v_mov_b64_e32 v[22:23], v[6:7]
	v_mov_b64_e32 v[24:25], v[8:9]
	v_mov_b64_e32 v[26:27], v[10:11]
	v_mov_b64_e32 v[16:17], v[12:13]
	v_mov_b64_e32 v[18:19], v[14:15]
	s_cbranch_scc1 .LBB0_1710
.LBB0_1676:
	s_add_i32 s21, s19, 1
	s_waitcnt vmcnt(0)
	v_mov_b64_e32 v[38:39], v[84:85]
	v_mov_b64_e32 v[32:33], v[92:93]
	v_mov_b64_e32 v[34:35], v[90:91]
	v_mov_b64_e32 v[36:37], v[88:89]
	v_lshlrev_b32_e32 v40, 16, v38
	v_and_b32_e32 v41, 0xffff0000, v38
	v_lshlrev_b32_e32 v38, 16, v39
	v_and_b32_e32 v39, 0xffff0000, v39
	v_lshlrev_b32_e32 v54, 16, v36
	v_and_b32_e32 v55, 0xffff0000, v36
	v_lshlrev_b32_e32 v94, 16, v37
	v_and_b32_e32 v95, 0xffff0000, v37
	v_lshlrev_b32_e32 v96, 16, v34
	v_and_b32_e32 v97, 0xffff0000, v34
	v_lshlrev_b32_e32 v100, 16, v35
	v_and_b32_e32 v101, 0xffff0000, v35
	v_lshlrev_b32_e32 v102, 16, v32
	v_and_b32_e32 v103, 0xffff0000, v32
	v_lshlrev_b32_e32 v104, 16, v33
	v_and_b32_e32 v105, 0xffff0000, v33
	v_pk_fma_f32 v[106:107], v[30:31], s[20:21], v[38:39] op_sel_hi:[1,0,1]
	global_load_dwordx4 v[30:33], v[66:67], off
	global_load_dwordx4 v[34:37], v[68:69], off
	v_pk_fma_f32 v[28:29], v[28:29], s[20:21], v[40:41] op_sel_hi:[1,0,1]
	v_pk_fma_f32 v[20:21], v[20:21], s[20:21], v[54:55] op_sel_hi:[1,0,1]
	v_add_f32_e32 v38, v28, v29
	v_add_f32_e32 v38, v38, v106
	v_pk_fma_f32 v[22:23], v[22:23], s[20:21], v[94:95] op_sel_hi:[1,0,1]
	v_add_f32_e32 v54, v20, v21
	v_pk_fma_f32 v[24:25], v[24:25], s[20:21], v[96:97] op_sel_hi:[1,0,1]
	v_add_f32_e32 v38, v107, v38
	v_add_f32_e32 v54, v54, v22
	v_pk_fma_f32 v[26:27], v[26:27], s[20:21], v[100:101] op_sel_hi:[1,0,1]
	v_add_f32_e32 v55, v24, v25
	v_add_f32_e32 v98, 0, v38
	v_add_f32_e32 v54, v23, v54
	v_add_f32_e32 v55, v55, v26
	v_add_f32_e32 v54, v98, v54
	v_add_f32_e32 v55, v27, v55
	v_pk_fma_f32 v[16:17], v[16:17], s[20:21], v[102:103] op_sel_hi:[1,0,1]
	v_add_f32_e32 v54, v54, v55
	v_pk_fma_f32 v[18:19], v[18:19], s[20:21], v[104:105] op_sel_hi:[1,0,1]
	v_add_f32_e32 v55, v16, v17
	v_add_f32_e32 v55, v55, v18
	v_add_f32_e32 v55, v19, v55
	v_add_f32_e32 v54, v54, v55
	ds_read_b128 v[38:41], v60
	ds_read_b128 v[42:45], v60 offset:4096
	ds_read_b128 v[46:49], v60 offset:8192
	ds_read_b128 v[50:53], v60 offset:12288
	ds_read_b128 v[108:111], v60 offset:16384
	ds_read_b128 v[122:125], v60 offset:20480
	ds_read_b128 v[130:133], v60 offset:24576
	ds_read_b128 v[134:137], v60 offset:28672
	ds_read_b128 v[138:141], v60 offset:32768
	ds_read_b128 v[142:145], v60 offset:36864
	ds_read_b128 v[146:149], v60 offset:40960
	ds_read_b128 v[150:153], v60 offset:45056
	ds_read_b128 v[154:157], v60 offset:49152
	v_add_f32_dpp v54, v54, v54 quad_perm:[1,0,3,2] row_mask:0xf bank_mask:0xf bound_ctrl:1
	s_nop 1
	v_add_f32_dpp v54, v54, v54 quad_perm:[2,3,0,1] row_mask:0xf bank_mask:0xf bound_ctrl:1
	s_nop 1
	v_add_f32_dpp v54, v54, v54 row_half_mirror row_mask:0xf bank_mask:0xf bound_ctrl:1
	s_nop 1
	v_add_f32_dpp v54, v54, v54 row_mirror row_mask:0xf bank_mask:0xf bound_ctrl:1
	s_nop 0
	v_readlane_b32 s2, v54, 16
	v_readlane_b32 s10, v54, 48
	v_readlane_b32 s0, v54, 0
	v_readlane_b32 s1, v54, 32
	v_mov_b32_e32 v54, s2
	v_mov_b32_e32 v55, s10
	v_pk_add_f32 v[54:55], s[0:1], v[54:55]
	s_nop 0
	v_add_f32_e32 v54, v54, v55
	v_mul_f32_e32 v54, 0x3a800000, v54
	v_pk_add_f32 v[28:29], v[28:29], v[54:55] op_sel_hi:[1,0] neg_lo:[0,1] neg_hi:[0,1]
	v_pk_add_f32 v[126:127], v[106:107], v[54:55] op_sel_hi:[1,0] neg_lo:[0,1] neg_hi:[0,1]
	v_pk_mul_f32 v[104:105], v[28:29], v[28:29]
	v_pk_mul_f32 v[106:107], v[126:127], v[126:127]
	v_pk_add_f32 v[158:159], v[20:21], v[54:55] op_sel_hi:[1,0] neg_lo:[0,1] neg_hi:[0,1]
	v_pk_add_f32 v[160:161], v[22:23], v[54:55] op_sel_hi:[1,0] neg_lo:[0,1] neg_hi:[0,1]
	v_pk_add_f32 v[100:101], v[24:25], v[54:55] op_sel_hi:[1,0] neg_lo:[0,1] neg_hi:[0,1]
	v_pk_add_f32 v[102:103], v[26:27], v[54:55] op_sel_hi:[1,0] neg_lo:[0,1] neg_hi:[0,1]
	v_pk_add_f32 v[94:95], v[16:17], v[54:55] op_sel_hi:[1,0] neg_lo:[0,1] neg_hi:[0,1]
	v_pk_add_f32 v[96:97], v[18:19], v[54:55] op_sel_hi:[1,0] neg_lo:[0,1] neg_hi:[0,1]
	v_add_f32_e32 v54, v104, v105
	v_add_f32_e32 v54, v106, v54
	v_pk_mul_f32 v[20:21], v[158:159], v[158:159]
	v_add_f32_e32 v54, v107, v54
	v_add_f32_e32 v20, v20, v54
	v_pk_mul_f32 v[22:23], v[160:161], v[160:161]
	v_add_f32_e32 v20, v21, v20
	v_add_f32_e32 v20, v22, v20
	v_pk_mul_f32 v[24:25], v[100:101], v[100:101]
	v_add_f32_e32 v20, v23, v20
	v_add_f32_e32 v20, v24, v20
	v_pk_mul_f32 v[26:27], v[102:103], v[102:103]
	v_add_f32_e32 v20, v25, v20
	v_add_f32_e32 v20, v26, v20
	v_pk_mul_f32 v[16:17], v[94:95], v[94:95]
	v_add_f32_e32 v20, v27, v20
	v_add_f32_e32 v16, v16, v20
	v_pk_mul_f32 v[18:19], v[96:97], v[96:97]
	v_add_f32_e32 v16, v17, v16
	v_add_f32_e32 v16, v18, v16
	v_add_f32_e32 v16, v19, v16
	s_nop 1
	v_add_f32_dpp v16, v16, v16 quad_perm:[1,0,3,2] row_mask:0xf bank_mask:0xf bound_ctrl:1
	s_nop 1
	v_add_f32_dpp v16, v16, v16 quad_perm:[2,3,0,1] row_mask:0xf bank_mask:0xf bound_ctrl:1
	s_nop 1
	v_add_f32_dpp v16, v16, v16 row_half_mirror row_mask:0xf bank_mask:0xf bound_ctrl:1
	s_nop 1
	v_add_f32_dpp v16, v16, v16 row_mirror row_mask:0xf bank_mask:0xf bound_ctrl:1
	s_nop 0
	v_readlane_b32 s2, v16, 16
	v_readlane_b32 s10, v16, 48
	v_readlane_b32 s0, v16, 0
	v_readlane_b32 s1, v16, 32
	v_mov_b32_e32 v16, s2
	v_mov_b32_e32 v17, s10
	v_pk_add_f32 v[16:17], s[0:1], v[16:17]
	s_mov_b32 s0, 0x800000
	v_add_f32_e32 v16, v16, v17
	v_fmamk_f32 v16, v16, 0x3a800000, v116
	v_cmp_gt_f32_e32 vcc, s0, v16
	v_mul_f32_e32 v17, 0x4b800000, v16
	s_nop 0
	v_cndmask_b32_e32 v16, v16, v17, vcc
	v_rsq_f32_e32 v54, v16
	ds_read_b128 v[16:19], v60 offset:53248
	ds_read_b128 v[20:23], v60 offset:57344
	ds_read_b128 v[24:27], v60 offset:61440
	v_mul_f32_e32 v55, 0x45800000, v54
	v_cndmask_b32_e32 v98, v54, v55, vcc
	v_pk_mul_f32 v[28:29], v[28:29], v[98:99] op_sel_hi:[1,0]
	s_waitcnt vmcnt(0)
	v_pk_fma_f32 v[106:107], v[30:31], v[28:29], v[34:35]
	v_pk_mul_f32 v[28:29], v[126:127], v[98:99] op_sel_hi:[1,0]
	s_waitcnt lgkmcnt(2)
	v_mul_f32_e32 v17, v107, v17
	v_pk_fma_f32 v[104:105], v[32:33], v[28:29], v[36:37]
	v_cvt_pk_bf16_f32 v28, v106, v107
	v_cvt_pk_bf16_f32 v29, v104, v105
	global_store_dwordx2 v[86:87], v[28:29], off offset:-1024
	v_mul_f32_e32 v28, v39, v107
	v_fmac_f32_e32 v28, v38, v106
	global_load_dwordx4 v[32:35], v[66:67], off offset:1024
	global_load_dwordx4 v[36:39], v[68:69], off offset:1024
	v_fmac_f32_e32 v28, v104, v40
	v_fmac_f32_e32 v28, v105, v41
	v_add_f32_e32 v54, 0, v28
	v_mul_f32_e32 v28, v107, v43
	v_fmac_f32_e32 v28, v106, v42
	v_fmac_f32_e32 v28, v104, v44
	v_fmac_f32_e32 v28, v105, v45
	v_add_f32_e32 v55, 0, v28
	v_mul_f32_e32 v28, v107, v47
	v_fmac_f32_e32 v28, v106, v46
	v_fmac_f32_e32 v28, v104, v48
	v_fmac_f32_e32 v28, v105, v49
	v_add_f32_e32 v46, 0, v28
	v_mul_f32_e32 v28, v107, v51
	v_fmac_f32_e32 v28, v106, v50
	v_fmac_f32_e32 v28, v104, v52
	v_fmac_f32_e32 v28, v105, v53
	v_add_f32_e32 v45, 0, v28
	v_mul_f32_e32 v28, v107, v109
	v_fmac_f32_e32 v28, v106, v108
	v_fmac_f32_e32 v28, v104, v110
	v_fmac_f32_e32 v28, v105, v111
	v_add_f32_e32 v44, 0, v28
	v_mul_f32_e32 v28, v107, v123
	v_fmac_f32_e32 v28, v106, v122
	v_fmac_f32_e32 v28, v104, v124
	v_fmac_f32_e32 v28, v105, v125
	v_add_f32_e32 v53, 0, v28
	v_mul_f32_e32 v28, v107, v131
	v_fmac_f32_e32 v28, v106, v130
	v_fmac_f32_e32 v28, v104, v132
	v_fmac_f32_e32 v28, v105, v133
	v_add_f32_e32 v52, 0, v28
	v_mul_f32_e32 v28, v107, v135
	v_fmac_f32_e32 v28, v106, v134
	v_fmac_f32_e32 v28, v104, v136
	v_fmac_f32_e32 v28, v105, v137
	v_add_f32_e32 v51, 0, v28
	v_mul_f32_e32 v28, v107, v139
	v_fmac_f32_e32 v28, v106, v138
	v_fmac_f32_e32 v28, v104, v140
	v_fmac_f32_e32 v28, v105, v141
	v_add_f32_e32 v50, 0, v28
	v_mul_f32_e32 v28, v107, v143
	v_fmac_f32_e32 v28, v106, v142
	v_fmac_f32_e32 v28, v104, v144
	v_fmac_f32_e32 v28, v105, v145
	v_add_f32_e32 v49, 0, v28
	v_mul_f32_e32 v28, v107, v147
	v_fmac_f32_e32 v28, v106, v146
	v_fmac_f32_e32 v28, v104, v148
	v_fmac_f32_e32 v28, v105, v149
	v_add_f32_e32 v48, 0, v28
	v_mul_f32_e32 v28, v107, v151
	v_fmac_f32_e32 v17, v106, v16
	s_waitcnt lgkmcnt(1)
	v_mul_f32_e32 v16, v107, v21
	v_fmac_f32_e32 v28, v106, v150
	v_fmac_f32_e32 v16, v106, v20
	v_fmac_f32_e32 v28, v104, v152
	v_fmac_f32_e32 v16, v104, v22
	v_fmac_f32_e32 v28, v105, v153
	v_fmac_f32_e32 v16, v105, v23
	v_add_f32_e32 v131, 0, v28
	v_mul_f32_e32 v28, v107, v155
	v_add_f32_e32 v122, 0, v16
	s_waitcnt lgkmcnt(0)
	v_mul_f32_e32 v16, v107, v25
	v_fmac_f32_e32 v28, v106, v154
	v_fmac_f32_e32 v16, v106, v24
	v_fmac_f32_e32 v28, v104, v156
	v_fmac_f32_e32 v17, v104, v18
	v_fmac_f32_e32 v16, v104, v26
	v_fmac_f32_e32 v28, v105, v157
	v_fmac_f32_e32 v17, v105, v19
	v_fmac_f32_e32 v16, v105, v27
	v_pk_mul_f32 v[40:41], v[158:159], v[98:99] op_sel_hi:[1,0]
	v_add_f32_e32 v125, 0, v28
	v_add_f32_e32 v124, 0, v17
	v_add_f32_e32 v123, 0, v16
	global_load_dwordx4 v[16:19], v[72:73], off offset:48
	global_load_dwordx4 v[20:23], v[72:73], off offset:32
	global_load_dwordx4 v[24:27], v[72:73], off offset:16
	global_load_dwordx4 v[28:31], v[72:73], off
	s_waitcnt vmcnt(4)
	v_pk_fma_f32 v[108:109], v[40:41], v[32:33], v[36:37]
	ds_read_b128 v[40:43], v60 offset:1024
	ds_read_b128 v[134:137], v60 offset:21504
	v_pk_mul_f32 v[32:33], v[160:161], v[98:99] op_sel_hi:[1,0]
	ds_read_b128 v[142:145], v60 offset:29696
	v_pk_fma_f32 v[110:111], v[32:33], v[34:35], v[38:39]
	s_waitcnt lgkmcnt(2)
	v_mul_f32_e32 v36, v109, v41
	v_cvt_pk_bf16_f32 v32, v108, v109
	v_cvt_pk_bf16_f32 v33, v110, v111
	v_fmac_f32_e32 v36, v108, v40
	global_store_dwordx2 v[86:87], v[32:33], off offset:-512
	ds_read_b128 v[32:35], v60 offset:5120
	v_fmac_f32_e32 v36, v110, v42
	v_fmac_f32_e32 v36, v111, v43
	v_add_f32_e32 v126, v54, v36
	s_waitcnt lgkmcnt(2)
	v_mul_f32_e32 v54, v109, v135
	s_waitcnt lgkmcnt(1)
	v_mul_f32_e32 v135, v109, v143
	v_fmac_f32_e32 v135, v108, v142
	v_fmac_f32_e32 v135, v110, v144
	v_fmac_f32_e32 v135, v111, v145
	ds_read_b128 v[144:147], v60 offset:50176
	s_waitcnt lgkmcnt(1)
	v_mul_f32_e32 v33, v109, v33
	v_fmac_f32_e32 v33, v108, v32
	v_fmac_f32_e32 v33, v110, v34
	v_fmac_f32_e32 v33, v111, v35
	ds_read_b128 v[36:39], v60 offset:9216
	v_add_f32_e32 v127, v55, v33
	ds_read_b128 v[32:35], v60 offset:13312
	ds_read_b128 v[40:43], v60 offset:17408
	ds_read_b128 v[138:141], v60 offset:25600
	v_fmac_f32_e32 v54, v108, v134
	v_fmac_f32_e32 v54, v110, v136
	s_waitcnt lgkmcnt(3)
	v_mul_f32_e32 v37, v109, v37
	s_waitcnt lgkmcnt(2)
	v_mul_f32_e32 v33, v109, v33
	v_fmac_f32_e32 v54, v111, v137
	v_fmac_f32_e32 v37, v108, v36
	v_fmac_f32_e32 v33, v108, v32
	v_add_f32_e32 v133, v53, v54
	s_waitcnt lgkmcnt(0)
	v_mul_f32_e32 v53, v109, v139
	v_fmac_f32_e32 v37, v110, v38
	v_fmac_f32_e32 v33, v110, v34
	v_mul_f32_e32 v41, v109, v41
	v_fmac_f32_e32 v53, v108, v138
	v_fmac_f32_e32 v37, v111, v39
	v_fmac_f32_e32 v33, v111, v35
	v_fmac_f32_e32 v41, v108, v40
	v_fmac_f32_e32 v53, v110, v140
	v_add_f32_e32 v129, v46, v37
	v_add_f32_e32 v130, v45, v33
	global_load_dwordx4 v[32:35], v[74:75], off
	global_load_dwordx4 v[36:39], v[74:75], off offset:16
	v_fmac_f32_e32 v41, v110, v42
	v_fmac_f32_e32 v53, v111, v141
	v_fmac_f32_e32 v41, v111, v43
	v_add_f32_e32 v134, v52, v53
	ds_read_b128 v[52:55], v60 offset:33792
	ds_read_b128 v[138:141], v60 offset:37888
	v_add_f32_e32 v132, v44, v41
	global_load_dwordx4 v[40:43], v[74:75], off offset:32
	global_load_dwordx4 v[44:47], v[74:75], off offset:48
	v_add_f32_e32 v135, v51, v135
	s_waitcnt lgkmcnt(1)
	v_mul_f32_e32 v51, v109, v53
	v_fmac_f32_e32 v51, v108, v52
	v_fmac_f32_e32 v51, v110, v54
	v_fmac_f32_e32 v51, v111, v55
	v_add_f32_e32 v136, v50, v51
	ds_read_b128 v[50:53], v60 offset:41984
	s_waitcnt lgkmcnt(1)
	v_mul_f32_e32 v54, v109, v139
	v_fmac_f32_e32 v54, v108, v138
	v_fmac_f32_e32 v54, v110, v140
	v_fmac_f32_e32 v54, v111, v141
	v_add_f32_e32 v137, v49, v54
	ds_read_b128 v[140:143], v60 offset:46080
	s_waitcnt lgkmcnt(1)
	v_mul_f32_e32 v49, v109, v51
	v_fmac_f32_e32 v49, v108, v50
	v_fmac_f32_e32 v49, v110, v52
	v_fmac_f32_e32 v49, v111, v53
	v_add_f32_e32 v138, v48, v49
	global_load_dwordx4 v[48:51], v[66:67], off offset:2048
	global_load_dwordx4 v[52:55], v[68:69], off offset:2048
	s_waitcnt lgkmcnt(0)
	v_mul_f32_e32 v139, v109, v141
	v_fmac_f32_e32 v139, v108, v140
	v_fmac_f32_e32 v139, v110, v142
	v_fmac_f32_e32 v139, v111, v143
	ds_read_b128 v[140:143], v60 offset:54272
	v_add_f32_e32 v131, v131, v139
	v_mul_f32_e32 v139, v109, v145
	v_fmac_f32_e32 v139, v108, v144
	v_fmac_f32_e32 v139, v110, v146
	v_fmac_f32_e32 v139, v111, v147
	ds_read_b128 v[144:147], v60 offset:58368
	v_add_f32_e32 v139, v125, v139
	s_waitcnt lgkmcnt(1)
	v_mul_f32_e32 v125, v109, v141
	v_fmac_f32_e32 v125, v108, v140
	v_fmac_f32_e32 v125, v110, v142
	v_fmac_f32_e32 v125, v111, v143
	ds_read_b128 v[140:143], v60 offset:62464
	v_add_f32_e32 v148, v124, v125
	s_waitcnt lgkmcnt(1)
	v_mul_f32_e32 v124, v109, v145
	v_fmac_f32_e32 v124, v108, v144
	v_fmac_f32_e32 v124, v110, v146
	v_fmac_f32_e32 v124, v111, v147
	v_add_f32_e32 v144, v122, v124
	s_waitcnt lgkmcnt(0)
	v_mul_f32_e32 v122, v109, v141
	v_fmac_f32_e32 v122, v108, v140
	v_fmac_f32_e32 v122, v110, v142
	v_fmac_f32_e32 v122, v111, v143
	v_add_f32_e32 v142, v123, v122
	v_mov_b32_e32 v122, v106
	v_mov_b32_e32 v123, v108
	v_mov_b32_e32 v108, v107
	s_waitcnt vmcnt(8)
	v_mov_b32_e32 v106, v24
	s_waitcnt vmcnt(7)
	v_mov_b32_e32 v124, v28
	v_mov_b32_e32 v140, v20
	s_waitcnt vmcnt(5)
	v_mov_b32_e32 v125, v32
	s_waitcnt vmcnt(4)
	v_mov_b32_e32 v107, v36
	v_pk_mul_f32 v[106:107], v[108:109], v[106:107]
	v_mov_b32_e32 v36, v25
	v_pk_fma_f32 v[106:107], v[122:123], v[124:125], v[106:107]
	v_mov_b32_e32 v124, v104
	v_mov_b32_e32 v125, v110
	v_mov_b32_e32 v110, v105
	v_mov_b32_e32 v104, v16
	s_waitcnt vmcnt(3)
	v_mov_b32_e32 v141, v40
	v_pk_fma_f32 v[106:107], v[124:125], v[140:141], v[106:107]
	s_waitcnt vmcnt(2)
	v_mov_b32_e32 v105, v44
	v_mov_b32_e32 v32, v29
	v_pk_mul_f32 v[24:25], v[108:109], v[36:37]
	v_pk_fma_f32 v[104:105], v[110:111], v[104:105], v[106:107]
	v_pk_fma_f32 v[24:25], v[122:123], v[32:33], v[24:25]
	v_mov_b32_e32 v40, v21
	v_add_f32_e32 v16, 0, v104
	v_pk_fma_f32 v[20:21], v[124:125], v[40:41], v[24:25]
	v_mov_b32_e32 v44, v17
	v_add_f32_e32 v107, v16, v105
	v_pk_fma_f32 v[16:17], v[110:111], v[44:45], v[20:21]
	v_mov_b32_e32 v20, v26
	v_add_f32_e32 v16, 0, v16
	v_mov_b32_e32 v21, v38
	v_add_f32_e32 v105, v16, v17
	v_mov_b32_e32 v16, v30
	v_mov_b32_e32 v17, v34
	v_pk_mul_f32 v[20:21], v[108:109], v[20:21]
	v_mov_b32_e32 v38, v27
	v_pk_fma_f32 v[16:17], v[122:123], v[16:17], v[20:21]
	v_mov_b32_e32 v20, v22
	v_mov_b32_e32 v21, v42
	v_pk_fma_f32 v[16:17], v[124:125], v[20:21], v[16:17]
	v_mov_b32_e32 v20, v18
	v_mov_b32_e32 v21, v46
	v_pk_fma_f32 v[16:17], v[110:111], v[20:21], v[16:17]
	v_mov_b32_e32 v34, v31
	v_add_f32_e32 v16, 0, v16
	v_add_f32_e32 v106, v16, v17
	v_pk_mul_f32 v[16:17], v[108:109], v[38:39]
	v_mov_b32_e32 v42, v23
	v_pk_fma_f32 v[16:17], v[122:123], v[34:35], v[16:17]
	v_mov_b32_e32 v46, v19
	v_pk_fma_f32 v[16:17], v[124:125], v[42:43], v[16:17]
	v_pk_mul_f32 v[20:21], v[102:103], v[98:99] op_sel_hi:[1,0]
	v_pk_fma_f32 v[16:17], v[110:111], v[46:47], v[16:17]
	s_waitcnt vmcnt(0)
	v_pk_fma_f32 v[50:51], v[20:21], v[50:51], v[54:55]
	v_add_f32_e32 v16, 0, v16
	v_add_f32_e32 v104, v16, v17
	v_pk_mul_f32 v[16:17], v[100:101], v[98:99] op_sel_hi:[1,0]
	v_cvt_pk_bf16_f32 v21, v50, v51
	v_pk_fma_f32 v[48:49], v[16:17], v[48:49], v[52:53]
	ds_read_b128 v[16:19], v60 offset:2048
	v_cvt_pk_bf16_f32 v20, v48, v49
	global_store_dwordx2 v[86:87], v[20:21], off
	ds_read_b128 v[20:23], v60 offset:6144
	v_pk_mul_f32 v[46:47], v[94:95], v[98:99] op_sel_hi:[1,0]
	s_waitcnt lgkmcnt(1)
	v_mul_f32_e32 v17, v49, v17
	v_fmac_f32_e32 v17, v48, v16
	v_fmac_f32_e32 v17, v50, v18
	v_fmac_f32_e32 v17, v51, v19
	v_add_f32_e32 v42, v126, v17
	ds_read_b128 v[16:19], v60 offset:10240
	s_waitcnt lgkmcnt(1)
	v_mul_f32_e32 v21, v49, v21
	v_fmac_f32_e32 v21, v48, v20
	v_fmac_f32_e32 v21, v50, v22
	v_fmac_f32_e32 v21, v51, v23
	v_add_f32_e32 v41, v127, v21
	ds_read_b128 v[20:23], v60 offset:14336
	s_waitcnt lgkmcnt(1)
	v_mul_f32_e32 v17, v49, v17
	v_fmac_f32_e32 v17, v48, v16
	v_fmac_f32_e32 v17, v50, v18
	v_fmac_f32_e32 v17, v51, v19
	v_add_f32_e32 v40, v129, v17
	ds_read_b128 v[16:19], v60 offset:18432
	global_load_dwordx4 v[32:35], v[66:67], off offset:3072
	global_load_dwordx4 v[36:39], v[68:69], off offset:3072
	s_waitcnt lgkmcnt(1)
	v_mul_f32_e32 v21, v49, v21
	v_fmac_f32_e32 v21, v48, v20
	v_fmac_f32_e32 v21, v50, v22
	v_fmac_f32_e32 v21, v51, v23
	v_add_f32_e32 v45, v130, v21
	ds_read_b128 v[20:23], v60 offset:22528
	s_waitcnt lgkmcnt(1)
	v_mul_f32_e32 v17, v49, v17
	v_fmac_f32_e32 v17, v48, v16
	v_fmac_f32_e32 v17, v50, v18
	v_fmac_f32_e32 v17, v51, v19
	v_add_f32_e32 v44, v132, v17
	ds_read_b128 v[16:19], v60 offset:26624
	s_waitcnt lgkmcnt(1)
	v_mul_f32_e32 v21, v49, v21
	v_fmac_f32_e32 v21, v48, v20
	v_fmac_f32_e32 v21, v50, v22
	v_fmac_f32_e32 v21, v51, v23
	v_add_f32_e32 v124, v133, v21
	ds_read_b128 v[20:23], v60 offset:30720
	s_waitcnt lgkmcnt(1)
	v_mul_f32_e32 v17, v49, v17
	v_fmac_f32_e32 v17, v48, v16
	v_fmac_f32_e32 v17, v50, v18
	v_fmac_f32_e32 v17, v51, v19
	s_waitcnt lgkmcnt(0)
	v_mul_f32_e32 v21, v49, v21
	v_fmac_f32_e32 v21, v48, v20
	v_fmac_f32_e32 v21, v50, v22
	v_add_f32_e32 v123, v134, v17
	ds_read_b128 v[16:19], v60 offset:34816
	v_fmac_f32_e32 v21, v51, v23
	v_add_f32_e32 v122, v135, v21
	ds_read_b128 v[20:23], v60 offset:38912
	s_waitcnt lgkmcnt(1)
	v_mul_f32_e32 v17, v49, v17
	v_fmac_f32_e32 v17, v48, v16
	v_fmac_f32_e32 v17, v50, v18
	s_waitcnt lgkmcnt(0)
	v_mul_f32_e32 v21, v49, v21
	v_fmac_f32_e32 v21, v48, v20
	v_fmac_f32_e32 v17, v51, v19
	v_fmac_f32_e32 v21, v50, v22
	v_add_f32_e32 v111, v136, v17
	ds_read_b128 v[16:19], v60 offset:43008
	v_fmac_f32_e32 v21, v51, v23
	v_add_f32_e32 v110, v137, v21
	ds_read_b128 v[20:23], v60 offset:47104
	s_waitcnt lgkmcnt(1)
	v_mul_f32_e32 v17, v49, v17
	v_fmac_f32_e32 v17, v48, v16
	v_fmac_f32_e32 v17, v50, v18
	s_waitcnt lgkmcnt(0)
	v_mul_f32_e32 v21, v49, v21
	v_fmac_f32_e32 v21, v48, v20
	v_fmac_f32_e32 v17, v51, v19
	v_fmac_f32_e32 v21, v50, v22
	v_add_f32_e32 v109, v138, v17
	ds_read_b128 v[16:19], v60 offset:51200
	v_fmac_f32_e32 v21, v51, v23
	v_add_f32_e32 v108, v131, v21
	ds_read_b128 v[20:23], v60 offset:55296
	s_waitcnt lgkmcnt(1)
	v_mul_f32_e32 v17, v49, v17
	v_fmac_f32_e32 v17, v48, v16
	v_fmac_f32_e32 v17, v50, v18
	s_waitcnt lgkmcnt(0)
	v_mul_f32_e32 v21, v49, v21
	v_fmac_f32_e32 v21, v48, v20
	v_fmac_f32_e32 v17, v51, v19
	v_fmac_f32_e32 v21, v50, v22
	v_add_f32_e32 v103, v139, v17
	ds_read_b128 v[16:19], v60 offset:59392
	v_fmac_f32_e32 v21, v51, v23
	v_add_f32_e32 v102, v148, v21
	ds_read_b128 v[20:23], v60 offset:63488
	s_waitcnt lgkmcnt(1)
	v_mul_f32_e32 v17, v49, v17
	v_fmac_f32_e32 v17, v48, v16
	v_fmac_f32_e32 v17, v50, v18
	s_waitcnt lgkmcnt(0)
	v_mul_f32_e32 v16, v49, v21
	v_fmac_f32_e32 v16, v48, v20
	v_fmac_f32_e32 v16, v50, v22
	v_fmac_f32_e32 v17, v51, v19
	v_fmac_f32_e32 v16, v51, v23
	v_add_f32_e32 v100, v144, v17
	v_add_f32_e32 v101, v142, v16
	global_load_dwordx4 v[16:19], v[76:77], off offset:48
	global_load_dwordx4 v[20:23], v[76:77], off offset:32
	global_load_dwordx4 v[24:27], v[76:77], off offset:16
	global_load_dwordx4 v[28:31], v[76:77], off
	s_waitcnt vmcnt(4)
	v_pk_fma_f32 v[52:53], v[46:47], v[32:33], v[36:37]
	v_pk_mul_f32 v[32:33], v[96:97], v[98:99] op_sel_hi:[1,0]
	ds_read_b128 v[94:97], v60 offset:3072
	v_pk_fma_f32 v[54:55], v[32:33], v[34:35], v[38:39]
	v_cvt_pk_bf16_f32 v32, v52, v53
	v_cvt_pk_bf16_f32 v33, v54, v55
	global_store_dwordx2 v[86:87], v[32:33], off offset:512
	ds_read_b128 v[32:35], v60 offset:7168
	s_waitcnt lgkmcnt(1)
	v_mul_f32_e32 v36, v53, v95
	v_fmac_f32_e32 v36, v52, v94
	v_fmac_f32_e32 v36, v54, v96
	v_fmac_f32_e32 v36, v55, v97
	v_add_f32_e32 v94, v42, v36
	ds_read_b128 v[36:39], v60 offset:11264
	ds_read_b128 v[130:133], v60 offset:15360
	s_waitcnt lgkmcnt(2)
	v_mul_f32_e32 v33, v53, v33
	v_fmac_f32_e32 v33, v52, v32
	v_fmac_f32_e32 v33, v54, v34
	s_waitcnt lgkmcnt(1)
	v_mul_f32_e32 v32, v53, v37
	v_fmac_f32_e32 v32, v52, v36
	v_fmac_f32_e32 v32, v54, v38
	v_fmac_f32_e32 v33, v55, v35
	v_fmac_f32_e32 v32, v55, v39
	v_add_f32_e32 v95, v41, v33
	v_add_f32_e32 v96, v40, v32
	ds_read_b128 v[40:43], v60 offset:19456
	s_waitcnt lgkmcnt(1)
	v_mul_f32_e32 v36, v53, v131
	v_fmac_f32_e32 v36, v52, v130
	v_fmac_f32_e32 v36, v54, v132
	v_fmac_f32_e32 v36, v55, v133
	v_add_f32_e32 v97, v45, v36
	ds_read_b128 v[130:133], v60 offset:23552
	s_waitcnt lgkmcnt(1)
	v_mul_f32_e32 v45, v53, v41
	global_load_dwordx4 v[32:35], v[78:79], off
	global_load_dwordx4 v[36:39], v[78:79], off offset:16
	v_fmac_f32_e32 v45, v52, v40
	v_fmac_f32_e32 v45, v54, v42
	v_fmac_f32_e32 v45, v55, v43
	global_load_dwordx4 v[40:43], v[78:79], off offset:32
	v_add_f32_e32 v125, v44, v45
	global_load_dwordx4 v[44:47], v[78:79], off offset:48
	ds_read_b128 v[134:137], v60 offset:27648
	s_waitcnt lgkmcnt(1)
	v_mul_f32_e32 v98, v53, v131
	v_fmac_f32_e32 v98, v52, v130
	v_fmac_f32_e32 v98, v54, v132
	v_fmac_f32_e32 v98, v55, v133
	ds_read_b128 v[130:133], v60 offset:31744
	v_add_f32_e32 v124, v124, v98
	s_waitcnt lgkmcnt(1)
	v_mul_f32_e32 v98, v53, v135
	v_fmac_f32_e32 v98, v52, v134
	v_fmac_f32_e32 v98, v54, v136
	v_fmac_f32_e32 v98, v55, v137
	ds_read_b128 v[134:137], v60 offset:35840
	v_add_f32_e32 v98, v123, v98
	s_waitcnt lgkmcnt(1)
	v_mul_f32_e32 v123, v53, v131
	v_fmac_f32_e32 v123, v52, v130
	v_fmac_f32_e32 v123, v54, v132
	v_fmac_f32_e32 v123, v55, v133
	ds_read_b128 v[130:133], v60 offset:39936
	v_add_f32_e32 v122, v122, v123
	s_waitcnt lgkmcnt(1)
	v_mul_f32_e32 v123, v53, v135
	v_fmac_f32_e32 v123, v52, v134
	v_fmac_f32_e32 v123, v54, v136
	v_fmac_f32_e32 v123, v55, v137
	ds_read_b128 v[134:137], v60 offset:44032
	v_add_f32_e32 v111, v111, v123
	s_waitcnt lgkmcnt(1)
	v_mul_f32_e32 v123, v53, v131
	v_fmac_f32_e32 v123, v52, v130
	v_fmac_f32_e32 v123, v54, v132
	v_fmac_f32_e32 v123, v55, v133
	ds_read_b128 v[130:133], v60 offset:48128
	v_add_f32_e32 v110, v110, v123
	s_waitcnt lgkmcnt(1)
	v_mul_f32_e32 v123, v53, v135
	v_fmac_f32_e32 v123, v52, v134
	v_fmac_f32_e32 v123, v54, v136
	v_fmac_f32_e32 v123, v55, v137
	ds_read_b128 v[134:137], v60 offset:52224
	v_add_f32_e32 v109, v109, v123
	s_waitcnt lgkmcnt(1)
	v_mul_f32_e32 v123, v53, v131
	v_fmac_f32_e32 v123, v52, v130
	v_fmac_f32_e32 v123, v54, v132
	v_fmac_f32_e32 v123, v55, v133
	ds_read_b128 v[130:133], v60 offset:56320
	v_add_f32_e32 v108, v108, v123
	s_waitcnt lgkmcnt(1)
	v_mul_f32_e32 v123, v53, v135
	v_fmac_f32_e32 v123, v52, v134
	v_fmac_f32_e32 v123, v54, v136
	v_fmac_f32_e32 v123, v55, v137
	ds_read_b128 v[134:137], v60 offset:60416
	v_add_f32_e32 v103, v103, v123
	s_waitcnt lgkmcnt(1)
	v_mul_f32_e32 v123, v53, v131
	v_fmac_f32_e32 v123, v52, v130
	v_fmac_f32_e32 v123, v54, v132
	v_fmac_f32_e32 v123, v55, v133
	ds_read_b128 v[130:133], v60 offset:64512
	v_add_f32_e32 v102, v102, v123
	s_waitcnt lgkmcnt(1)
	v_mul_f32_e32 v123, v53, v135
	v_fmac_f32_e32 v123, v52, v134
	v_fmac_f32_e32 v123, v54, v136
	v_fmac_f32_e32 v123, v55, v137
	v_add_f32_e32 v123, v100, v123
	s_waitcnt lgkmcnt(0)
	v_mul_f32_e32 v100, v53, v131
	v_fmac_f32_e32 v100, v52, v130
	v_fmac_f32_e32 v100, v54, v132
	v_fmac_f32_e32 v100, v55, v133
	v_add_f32_e32 v129, v101, v100
	v_mov_b32_e32 v100, v48
	v_mov_b32_e32 v101, v52
	v_mov_b32_e32 v52, v49
	s_waitcnt vmcnt(6)
	v_mov_b32_e32 v48, v24
	s_waitcnt vmcnt(5)
	v_mov_b32_e32 v126, v28
	v_mov_b32_e32 v130, v20
	s_waitcnt vmcnt(3)
	v_mov_b32_e32 v127, v32
	s_waitcnt vmcnt(2)
	v_mov_b32_e32 v49, v36
	v_pk_mul_f32 v[48:49], v[52:53], v[48:49]
	v_mov_b32_e32 v36, v25
	v_pk_fma_f32 v[48:49], v[100:101], v[126:127], v[48:49]
	v_mov_b32_e32 v126, v50
	v_mov_b32_e32 v127, v54
	s_waitcnt vmcnt(1)
	v_mov_b32_e32 v131, v40
	v_pk_fma_f32 v[48:49], v[126:127], v[130:131], v[48:49]
	v_mov_b32_e32 v54, v51
	v_mov_b32_e32 v50, v16
	s_waitcnt vmcnt(0)
	v_mov_b32_e32 v0, s21
	v_min_u32_e32 v0, 15, v0
	v_mov_b32_e32 v1, 0
	v_lshl_add_u64 v[0:1], v[82:83], 0, v[0:1]
	v_lshlrev_b64 v[2:3], 12, v[0:1]
	v_lshlrev_b64 v[0:1], 11, v[0:1]
	v_lshl_add_u64 v[12:13], v[62:63], 0, v[2:3]
	v_lshl_add_u64 v[92:93], v[64:65], 0, v[0:1]
	global_load_dwordx4 v[0:3], v[12:13], off
	global_load_dwordx2 v[84:85], v[92:93], off
	global_load_dwordx4 v[4:7], v[12:13], off offset:1024
	global_load_dwordx2 v[88:89], v[92:93], off offset:512
	global_load_dwordx4 v[8:11], v[12:13], off offset:2048
	global_load_dwordx2 v[90:91], v[92:93], off offset:1024
	s_nop 0
	global_load_dwordx4 v[12:15], v[12:13], off offset:3072
	s_nop 0
	global_load_dwordx2 v[92:93], v[92:93], off offset:1536
	v_mov_b32_e32 v51, v44
	v_mov_b32_e32 v32, v29
	v_pk_mul_f32 v[24:25], v[52:53], v[36:37]
	v_pk_fma_f32 v[48:49], v[54:55], v[50:51], v[48:49]
	v_pk_fma_f32 v[24:25], v[100:101], v[32:33], v[24:25]
	v_mov_b32_e32 v40, v21
	v_add_f32_e32 v16, v107, v48
	v_pk_fma_f32 v[20:21], v[126:127], v[40:41], v[24:25]
	v_mov_b32_e32 v44, v17
	v_add_f32_e32 v28, v16, v49
	v_pk_fma_f32 v[16:17], v[54:55], v[44:45], v[20:21]
	v_mov_b32_e32 v20, v26
	v_add_f32_e32 v16, v105, v16
	v_mov_b32_e32 v21, v38
	v_add_f32_e32 v24, v16, v17
	v_mov_b32_e32 v16, v30
	v_mov_b32_e32 v17, v34
	v_pk_mul_f32 v[20:21], v[52:53], v[20:21]
	v_mov_b32_e32 v38, v27
	v_pk_fma_f32 v[16:17], v[100:101], v[16:17], v[20:21]
	v_mov_b32_e32 v20, v22
	v_mov_b32_e32 v21, v42
	v_pk_fma_f32 v[16:17], v[126:127], v[20:21], v[16:17]
	v_mov_b32_e32 v20, v18
	v_mov_b32_e32 v21, v46
	v_pk_fma_f32 v[16:17], v[54:55], v[20:21], v[16:17]
	v_mov_b32_e32 v34, v31
	v_add_f32_e32 v16, v106, v16
	v_add_f32_e32 v20, v16, v17
	v_pk_mul_f32 v[16:17], v[52:53], v[38:39]
	v_mov_b32_e32 v42, v23
	v_pk_fma_f32 v[16:17], v[100:101], v[34:35], v[16:17]
	v_mov_b32_e32 v46, v19
	v_pk_fma_f32 v[16:17], v[126:127], v[42:43], v[16:17]
	v_add_f32_dpp v18, v24, v24 quad_perm:[1,0,3,2] row_mask:0xf bank_mask:0xf bound_ctrl:1
	v_pk_fma_f32 v[16:17], v[54:55], v[46:47], v[16:17]
	v_add_f32_dpp v20, v20, v20 quad_perm:[1,0,3,2] row_mask:0xf bank_mask:0xf bound_ctrl:1
	v_add_f32_e32 v16, v104, v16
	v_add_f32_e32 v22, v16, v17
	v_add_f32_dpp v18, v18, v18 quad_perm:[2,3,0,1] row_mask:0xf bank_mask:0xf bound_ctrl:1
	v_add_f32_dpp v16, v28, v28 quad_perm:[1,0,3,2] row_mask:0xf bank_mask:0xf bound_ctrl:1
	v_add_f32_dpp v20, v20, v20 quad_perm:[2,3,0,1] row_mask:0xf bank_mask:0xf bound_ctrl:1
	v_add_f32_dpp v18, v18, v18 row_half_mirror row_mask:0xf bank_mask:0xf bound_ctrl:1
	v_add_f32_dpp v16, v16, v16 quad_perm:[2,3,0,1] row_mask:0xf bank_mask:0xf bound_ctrl:1
	v_add_f32_dpp v20, v20, v20 row_half_mirror row_mask:0xf bank_mask:0xf bound_ctrl:1
	v_add_f32_dpp v18, v18, v18 row_mirror row_mask:0xf bank_mask:0xf bound_ctrl:1
	v_add_f32_dpp v16, v16, v16 row_half_mirror row_mask:0xf bank_mask:0xf bound_ctrl:1
	v_add_f32_dpp v20, v20, v20 row_mirror row_mask:0xf bank_mask:0xf bound_ctrl:1
	s_nop 0
	v_add_f32_dpp v16, v16, v16 row_mirror row_mask:0xf bank_mask:0xf bound_ctrl:1
	s_nop 0
	v_readlane_b32 s2, v16, 16
	v_readlane_b32 s10, v16, 48
	v_readlane_b32 s0, v16, 0
	v_readlane_b32 s1, v16, 32
	v_mov_b32_e32 v16, s2
	v_mov_b32_e32 v17, s10
	v_readlane_b32 s2, v18, 16
	v_readlane_b32 s10, v18, 48
	v_pk_add_f32 v[16:17], s[0:1], v[16:17]
	v_readlane_b32 s0, v18, 0
	v_readlane_b32 s1, v18, 32
	v_mov_b32_e32 v18, s2
	v_mov_b32_e32 v19, s10
	v_readlane_b32 s2, v20, 16
	v_readlane_b32 s10, v20, 48
	v_pk_add_f32 v[18:19], s[0:1], v[18:19]
	v_readlane_b32 s0, v20, 0
	v_readlane_b32 s1, v20, 32
	v_mov_b32_e32 v20, s2
	v_mov_b32_e32 v21, s10
	v_pk_add_f32 v[20:21], s[0:1], v[20:21]
	v_mov_b32_e32 v25, v18
	v_add_f32_e32 v26, v20, v21
	v_add_f32_dpp v20, v22, v22 quad_perm:[1,0,3,2] row_mask:0xf bank_mask:0xf bound_ctrl:1
	v_mov_b32_e32 v18, v17
	s_nop 0
	v_add_f32_dpp v20, v20, v20 quad_perm:[2,3,0,1] row_mask:0xf bank_mask:0xf bound_ctrl:1
	s_nop 1
	v_add_f32_dpp v20, v20, v20 row_half_mirror row_mask:0xf bank_mask:0xf bound_ctrl:1
	s_nop 1
	v_add_f32_dpp v20, v20, v20 row_mirror row_mask:0xf bank_mask:0xf bound_ctrl:1
	s_nop 0
	v_readlane_b32 s2, v20, 16
	v_readlane_b32 s10, v20, 48
	v_readlane_b32 s0, v20, 0
	v_readlane_b32 s1, v20, 32
	v_mov_b32_e32 v20, s2
	v_mov_b32_e32 v21, s10
	v_pk_add_f32 v[20:21], s[0:1], v[20:21]
	s_nop 0
	v_add_f32_e32 v27, v20, v21
	v_add_f32_dpp v20, v94, v94 quad_perm:[1,0,3,2] row_mask:0xf bank_mask:0xf bound_ctrl:1
	s_nop 1
	v_add_f32_dpp v20, v20, v20 quad_perm:[2,3,0,1] row_mask:0xf bank_mask:0xf bound_ctrl:1
	s_nop 1
	v_add_f32_dpp v20, v20, v20 row_half_mirror row_mask:0xf bank_mask:0xf bound_ctrl:1
	s_nop 1
	v_add_f32_dpp v20, v20, v20 row_mirror row_mask:0xf bank_mask:0xf bound_ctrl:1
	s_nop 0
	v_readlane_b32 s14, v20, 0
	v_readlane_b32 s94, v20, 16
	v_readlane_b32 s15, v20, 32
	v_readlane_b32 s95, v20, 48
	v_add_f32_dpp v20, v95, v95 quad_perm:[1,0,3,2] row_mask:0xf bank_mask:0xf bound_ctrl:1
	s_nop 1
	v_add_f32_dpp v20, v20, v20 quad_perm:[2,3,0,1] row_mask:0xf bank_mask:0xf bound_ctrl:1
	s_nop 1
	v_add_f32_dpp v20, v20, v20 row_half_mirror row_mask:0xf bank_mask:0xf bound_ctrl:1
	s_nop 1
	v_add_f32_dpp v20, v20, v20 row_mirror row_mask:0xf bank_mask:0xf bound_ctrl:1
	s_nop 0
	v_readlane_b32 s87, v20, 0
	v_readlane_b32 s91, v20, 16
	v_readlane_b32 s90, v20, 32
	v_readlane_b32 s92, v20, 48
	v_add_f32_dpp v20, v96, v96 quad_perm:[1,0,3,2] row_mask:0xf bank_mask:0xf bound_ctrl:1
	s_nop 1
	v_add_f32_dpp v20, v20, v20 quad_perm:[2,3,0,1] row_mask:0xf bank_mask:0xf bound_ctrl:1
	s_nop 1
	v_add_f32_dpp v20, v20, v20 row_half_mirror row_mask:0xf bank_mask:0xf bound_ctrl:1
	s_nop 1
	v_add_f32_dpp v20, v20, v20 row_mirror row_mask:0xf bank_mask:0xf bound_ctrl:1
	s_nop 0
	v_readlane_b32 s65, v20, 0
	v_readlane_b32 s75, v20, 16
	v_readlane_b32 s66, v20, 32
	v_readlane_b32 s78, v20, 48
	v_add_f32_dpp v20, v97, v97 quad_perm:[1,0,3,2] row_mask:0xf bank_mask:0xf bound_ctrl:1
	s_nop 1
	v_add_f32_dpp v20, v20, v20 quad_perm:[2,3,0,1] row_mask:0xf bank_mask:0xf bound_ctrl:1
	s_nop 1
	v_add_f32_dpp v20, v20, v20 row_half_mirror row_mask:0xf bank_mask:0xf bound_ctrl:1
	s_nop 1
	v_add_f32_dpp v20, v20, v20 row_mirror row_mask:0xf bank_mask:0xf bound_ctrl:1
	s_nop 0
	v_readlane_b32 s51, v20, 0
	v_readlane_b32 s53, v20, 16
	v_readlane_b32 s52, v20, 32
	v_readlane_b32 s54, v20, 48
	v_add_f32_dpp v20, v125, v125 quad_perm:[1,0,3,2] row_mask:0xf bank_mask:0xf bound_ctrl:1
	s_nop 1
	v_add_f32_dpp v20, v20, v20 quad_perm:[2,3,0,1] row_mask:0xf bank_mask:0xf bound_ctrl:1
	s_nop 1
	v_add_f32_dpp v20, v20, v20 row_half_mirror row_mask:0xf bank_mask:0xf bound_ctrl:1
	s_nop 1
	v_add_f32_dpp v20, v20, v20 row_mirror row_mask:0xf bank_mask:0xf bound_ctrl:1
	s_nop 0
	v_readlane_b32 s35, v20, 0
	v_readlane_b32 s37, v20, 16
	v_readlane_b32 s36, v20, 32
	v_readlane_b32 s38, v20, 48
	v_add_f32_dpp v20, v124, v124 quad_perm:[1,0,3,2] row_mask:0xf bank_mask:0xf bound_ctrl:1
	s_nop 1
	v_add_f32_dpp v20, v20, v20 quad_perm:[2,3,0,1] row_mask:0xf bank_mask:0xf bound_ctrl:1
	s_nop 1
	v_add_f32_dpp v20, v20, v20 row_half_mirror row_mask:0xf bank_mask:0xf bound_ctrl:1
	s_nop 1
	v_add_f32_dpp v24, v20, v20 row_mirror row_mask:0xf bank_mask:0xf bound_ctrl:1
	s_nop 0
	v_readlane_b32 s23, v24, 0
	v_readlane_b32 s27, v24, 16
	v_readlane_b32 s26, v24, 32
	v_readlane_b32 s93, v24, 48
	v_add_f32_dpp v24, v98, v98 quad_perm:[1,0,3,2] row_mask:0xf bank_mask:0xf bound_ctrl:1
	s_nop 1
	v_add_f32_dpp v24, v24, v24 quad_perm:[2,3,0,1] row_mask:0xf bank_mask:0xf bound_ctrl:1
	s_nop 1
	v_add_f32_dpp v24, v24, v24 row_half_mirror row_mask:0xf bank_mask:0xf bound_ctrl:1
	s_nop 1
	v_add_f32_dpp v24, v24, v24 row_mirror row_mask:0xf bank_mask:0xf bound_ctrl:1
	s_nop 0
	v_readlane_b32 s81, v24, 0
	v_readlane_b32 s83, v24, 16
	v_readlane_b32 s82, v24, 32
	v_readlane_b32 s84, v24, 48
	v_add_f32_dpp v24, v122, v122 quad_perm:[1,0,3,2] row_mask:0xf bank_mask:0xf bound_ctrl:1
	s_nop 1
	v_add_f32_dpp v24, v24, v24 quad_perm:[2,3,0,1] row_mask:0xf bank_mask:0xf bound_ctrl:1
	s_nop 1
	v_add_f32_dpp v24, v24, v24 row_half_mirror row_mask:0xf bank_mask:0xf bound_ctrl:1
	s_nop 1
	v_add_f32_dpp v24, v24, v24 row_mirror row_mask:0xf bank_mask:0xf bound_ctrl:1
	s_nop 0
	v_readlane_b32 s63, v24, 0
	v_readlane_b32 s67, v24, 16
	v_readlane_b32 s64, v24, 32
	v_readlane_b32 s70, v24, 48
	v_add_f32_dpp v24, v111, v111 quad_perm:[1,0,3,2] row_mask:0xf bank_mask:0xf bound_ctrl:1
	s_nop 1
	v_add_f32_dpp v24, v24, v24 quad_perm:[2,3,0,1] row_mask:0xf bank_mask:0xf bound_ctrl:1
	s_nop 1
	v_add_f32_dpp v24, v24, v24 row_half_mirror row_mask:0xf bank_mask:0xf bound_ctrl:1
	s_nop 1
	v_add_f32_dpp v24, v24, v24 row_mirror row_mask:0xf bank_mask:0xf bound_ctrl:1
	s_nop 0
	v_readlane_b32 s59, v24, 0
	v_readlane_b32 s61, v24, 16
	v_readlane_b32 s60, v24, 32
	v_readlane_b32 s62, v24, 48
	v_add_f32_dpp v24, v110, v110 quad_perm:[1,0,3,2] row_mask:0xf bank_mask:0xf bound_ctrl:1
	s_nop 1
	v_add_f32_dpp v24, v24, v24 quad_perm:[2,3,0,1] row_mask:0xf bank_mask:0xf bound_ctrl:1
	s_nop 1
	v_add_f32_dpp v24, v24, v24 row_half_mirror row_mask:0xf bank_mask:0xf bound_ctrl:1
	s_nop 1
	v_add_f32_dpp v24, v24, v24 row_mirror row_mask:0xf bank_mask:0xf bound_ctrl:1
	s_nop 0
	v_readlane_b32 s55, v24, 0
	v_readlane_b32 s57, v24, 16
	v_readlane_b32 s56, v24, 32
	v_readlane_b32 s58, v24, 48
	v_add_f32_dpp v24, v109, v109 quad_perm:[1,0,3,2] row_mask:0xf bank_mask:0xf bound_ctrl:1
	s_nop 1
	v_add_f32_dpp v24, v24, v24 quad_perm:[2,3,0,1] row_mask:0xf bank_mask:0xf bound_ctrl:1
	s_nop 1
	v_add_f32_dpp v24, v24, v24 row_half_mirror row_mask:0xf bank_mask:0xf bound_ctrl:1
	s_nop 1
	v_add_f32_dpp v24, v24, v24 row_mirror row_mask:0xf bank_mask:0xf bound_ctrl:1
	s_nop 0
	v_readlane_b32 s47, v24, 0
	v_readlane_b32 s49, v24, 16
	v_readlane_b32 s48, v24, 32
	v_readlane_b32 s50, v24, 48
	v_add_f32_dpp v24, v108, v108 quad_perm:[1,0,3,2] row_mask:0xf bank_mask:0xf bound_ctrl:1
	s_nop 1
	v_add_f32_dpp v24, v24, v24 quad_perm:[2,3,0,1] row_mask:0xf bank_mask:0xf bound_ctrl:1
	s_nop 1
	v_add_f32_dpp v24, v24, v24 row_half_mirror row_mask:0xf bank_mask:0xf bound_ctrl:1
	s_nop 1
	v_add_f32_dpp v24, v24, v24 row_mirror row_mask:0xf bank_mask:0xf bound_ctrl:1
	s_nop 0
	v_readlane_b32 s43, v24, 0
	v_readlane_b32 s45, v24, 16
	v_readlane_b32 s44, v24, 32
	v_readlane_b32 s46, v24, 48
	v_add_f32_dpp v24, v103, v103 quad_perm:[1,0,3,2] row_mask:0xf bank_mask:0xf bound_ctrl:1
	s_nop 1
	v_add_f32_dpp v24, v24, v24 quad_perm:[2,3,0,1] row_mask:0xf bank_mask:0xf bound_ctrl:1
	s_nop 1
	v_add_f32_dpp v24, v24, v24 row_half_mirror row_mask:0xf bank_mask:0xf bound_ctrl:1
	s_nop 1
	v_add_f32_dpp v24, v24, v24 row_mirror row_mask:0xf bank_mask:0xf bound_ctrl:1
	s_nop 0
	v_readlane_b32 s39, v24, 0
	v_readlane_b32 s41, v24, 16
	v_readlane_b32 s40, v24, 32
	v_readlane_b32 s42, v24, 48
	v_add_f32_dpp v24, v102, v102 quad_perm:[1,0,3,2] row_mask:0xf bank_mask:0xf bound_ctrl:1
	s_nop 1
	v_add_f32_dpp v24, v24, v24 quad_perm:[2,3,0,1] row_mask:0xf bank_mask:0xf bound_ctrl:1
	s_nop 1
	v_add_f32_dpp v24, v24, v24 row_half_mirror row_mask:0xf bank_mask:0xf bound_ctrl:1
	s_nop 1
	v_add_f32_dpp v24, v24, v24 row_mirror row_mask:0xf bank_mask:0xf bound_ctrl:1
	s_nop 0
	v_readlane_b32 s30, v24, 0
	v_readlane_b32 s33, v24, 16
	v_readlane_b32 s31, v24, 32
	v_readlane_b32 s34, v24, 48
	v_add_f32_dpp v24, v123, v123 quad_perm:[1,0,3,2] row_mask:0xf bank_mask:0xf bound_ctrl:1
	s_nop 1
	v_add_f32_dpp v24, v24, v24 quad_perm:[2,3,0,1] row_mask:0xf bank_mask:0xf bound_ctrl:1
	s_nop 1
	v_add_f32_dpp v24, v24, v24 row_half_mirror row_mask:0xf bank_mask:0xf bound_ctrl:1
	s_nop 1
	v_add_f32_dpp v28, v24, v24 row_mirror row_mask:0xf bank_mask:0xf bound_ctrl:1
	v_add_f32_dpp v24, v129, v129 quad_perm:[1,0,3,2] row_mask:0xf bank_mask:0xf bound_ctrl:1
	v_readlane_b32 s28, v28, 0
	v_readlane_b32 s29, v28, 16
	v_add_f32_dpp v24, v24, v24 quad_perm:[2,3,0,1] row_mask:0xf bank_mask:0xf bound_ctrl:1
	v_readlane_b32 s85, v28, 32
	v_readlane_b32 s86, v28, 48
	v_add_f32_dpp v24, v24, v24 row_half_mirror row_mask:0xf bank_mask:0xf bound_ctrl:1
	s_nop 1
	v_add_f32_dpp v29, v24, v24 row_mirror row_mask:0xf bank_mask:0xf bound_ctrl:1
	v_mov_b32_e32 v24, v16
	v_pk_add_f32 v[16:17], v[24:25], v[18:19]
	v_mov_b32_e32 v20, v178
	v_mov_b32_e32 v21, v179
	v_mov_b32_e32 v22, v180
	v_mov_b32_e32 v23, v181
	v_add_f32_e32 v19, v26, v22
	v_pk_add_f32 v[16:17], v[16:17], v[20:21]
	v_add_f32_e32 v18, v27, v23
	v_cmp_gt_f32_e32 vcc, v17, v16
	v_mov_b32_e32 v22, 0
	v_readlane_b32 s71, v29, 0
	v_cndmask_b32_e32 v20, v16, v17, vcc
	v_cmp_gt_f32_e64 s[12:13], v19, v20
	v_cndmask_b32_e64 v21, 0, 1, vcc
	s_and_b64 s[10:11], s[12:13], exec
	v_cndmask_b32_e64 v20, v20, v19, s[12:13]
	v_cmp_ngt_f32_e64 s[0:1], v18, v20
	v_readfirstlane_b32 s2, v21
	s_cselect_b32 s2, 2, s2
	s_and_b64 s[10:11], s[0:1], exec
	s_cselect_b32 s2, s2, 3
	s_cmp_eq_u32 s2, 0
	s_cselect_b64 s[24:25], -1, 0
	s_cmp_lg_u32 s2, 0
	v_mov_b32_e32 v21, 0
	v_readlane_b32 s79, v29, 16
	v_readlane_b32 s74, v29, 32
	v_readlane_b32 s80, v29, 48
	v_cmp_gt_f32_e64 s[10:11], v18, v20
	s_cbranch_scc0 .LBB0_1684
	v_cndmask_b32_e64 v23, 0, 1, s[24:25]
	v_cmp_ne_u32_e64 s[14:15], 1, v23
	s_andn2_b64 vcc, exec, s[24:25]
	s_cbranch_vccz .LBB0_1685

.LBB0_1681:
	v_mov_b32_e32 v22, s37
	v_mov_b32_e32 v25, s38
	v_add_f32_e32 v22, s35, v22
	v_add_f32_e32 v25, s36, v25
	v_add_f32_e32 v22, v22, v25
	v_mov_b32_e32 v25, v166
	v_add_f32_e32 v22, v22, v25
	v_cndmask_b32_e64 v25, 0, 1, s[24:25]
	v_cmp_ne_u32_e64 s[14:15], 1, v25
	s_andn2_b64 vcc, exec, s[24:25]
	s_cbranch_vccz .LBB0_1689

.LBB0_1683:
	v_mov_b32_e32 v24, v168
	v_mov_b32_e32 v25, s83
	v_mov_b32_e32 v26, s84
	v_add_f32_e32 v25, s81, v25
	v_add_f32_e32 v26, s82, v26
	v_add_f32_e32 v25, v25, v26
	v_add_f32_e32 v24, v25, v24
	s_and_b64 vcc, exec, s[14:15]
	s_cbranch_vccz .LBB0_1691
	s_branch .LBB0_1692
.LBB0_1684:
	v_mov_b32_e32 v22, s94
	v_mov_b32_e32 v23, s95
	v_pk_add_f32 v[22:23], s[14:15], v[22:23]
	s_nop 0
	v_add_f32_e32 v22, v22, v23
	v_mov_b32_e32 v23, v162
	v_add_f32_e32 v22, v22, v23
	v_cndmask_b32_e64 v23, 0, 1, s[24:25]
	v_cmp_ne_u32_e64 s[14:15], 1, v23
	s_andn2_b64 vcc, exec, s[24:25]
	s_cbranch_vccnz .LBB0_1678
.LBB0_1685:
	v_mov_b32_e32 v21, s91
	v_mov_b32_e32 v23, s92
	v_add_f32_e32 v21, s87, v21
	v_add_f32_e32 v23, s90, v23
	v_add_f32_e32 v21, v21, v23
	v_mov_b32_e32 v23, v163
	v_add_f32_e32 v21, v21, v23
	v_mov_b32_e32 v23, 0
	s_and_b64 vcc, exec, s[14:15]
	v_mov_b32_e32 v24, 0
	s_cbranch_vccnz .LBB0_1679
.LBB0_1686:
	v_mov_b32_e32 v24, s75
	v_mov_b32_e32 v25, s78
	v_add_f32_e32 v24, s65, v24
	v_add_f32_e32 v25, s66, v25
	v_add_f32_e32 v24, v24, v25
	v_mov_b32_e32 v25, v164
	v_add_f32_e32 v24, v24, v25
	s_and_b64 vcc, exec, s[14:15]
	s_cbranch_vccnz .LBB0_1680
.LBB0_1687:
	v_mov_b32_e32 v23, s53
	v_mov_b32_e32 v25, s54
	v_add_f32_e32 v23, s51, v23
	v_add_f32_e32 v25, s52, v25
	v_add_f32_e32 v23, v23, v25
	v_mov_b32_e32 v25, v165
	v_add_f32_e32 v23, v23, v25
	s_cmp_eq_u32 s2, 1
	s_cselect_b64 s[24:25], -1, 0
	s_cmp_lg_u32 s2, 1
	s_cbranch_scc0 .LBB0_1681

.LBB0_1689:
	v_mov_b32_e32 v21, s27
	v_mov_b32_e32 v25, s93
	v_add_f32_e32 v21, s23, v21
	v_add_f32_e32 v25, s26, v25
	v_add_f32_e32 v21, v21, v25
	v_mov_b32_e32 v25, v167
	v_add_f32_e32 v21, v21, v25
	s_and_b64 vcc, exec, s[14:15]
	s_cbranch_vccz .LBB0_1683

.LBB0_1691:
	v_mov_b32_e32 v23, v169
	v_mov_b32_e32 v25, s67
	v_mov_b32_e32 v26, s70
	v_add_f32_e32 v25, s63, v25
	v_add_f32_e32 v26, s64, v26
	v_add_f32_e32 v25, v25, v26
	v_add_f32_e32 v23, v25, v23
.LBB0_1692:
	s_and_b64 s[14:15], s[12:13], s[0:1]
	v_cndmask_b32_e64 v25, 0, 1, s[14:15]
	v_cmp_ne_u32_e64 s[12:13], 1, v25
	s_andn2_b64 vcc, exec, s[14:15]
	s_cbranch_vccnz .LBB0_1701
	v_mov_b32_e32 v22, v170
	v_mov_b32_e32 v25, s61
	v_mov_b32_e32 v26, s62
	v_add_f32_e32 v25, s59, v25
	v_add_f32_e32 v26, s60, v26
	v_add_f32_e32 v25, v25, v26
	v_add_f32_e32 v22, v25, v22
	s_and_b64 vcc, exec, s[12:13]
	s_cbranch_vccz .LBB0_1702

.LBB0_1695:
	v_mov_b32_e32 v24, v172
	v_mov_b32_e32 v25, s49
	v_mov_b32_e32 v26, s50
	v_add_f32_e32 v25, s47, v25
	v_add_f32_e32 v26, s48, v26
	v_add_f32_e32 v25, v25, v26
	v_add_f32_e32 v24, v25, v24
	s_and_b64 vcc, exec, s[12:13]
	s_cbranch_vccz .LBB0_1704

.LBB0_1697:
	v_mov_b32_e32 v22, v174
	v_mov_b32_e32 v25, s41
	v_mov_b32_e32 v26, s42
	v_add_f32_e32 v25, s39, v25
	v_add_f32_e32 v26, s40, v26
	v_add_f32_e32 v25, v25, v26
	v_add_f32_e32 v22, v25, v22
	s_and_b64 vcc, exec, s[12:13]
	s_cbranch_vccz .LBB0_1706

.LBB0_1699:
	v_mov_b32_e32 v24, v176
	v_mov_b32_e32 v25, s29
	v_mov_b32_e32 v26, s86
	v_add_f32_e32 v25, s28, v25
	v_add_f32_e32 v26, s85, v26
	v_add_f32_e32 v25, v25, v26
	v_add_f32_e32 v24, v25, v24
	s_and_b64 vcc, exec, s[12:13]
	s_cbranch_vccz .LBB0_1708

.LBB0_1702:
	v_mov_b32_e32 v21, v171
	v_mov_b32_e32 v25, s57
	v_mov_b32_e32 v26, s58
	v_add_f32_e32 v25, s55, v25
	v_add_f32_e32 v26, s56, v26
	v_add_f32_e32 v25, v25, v26
	v_add_f32_e32 v21, v25, v21
	s_and_b64 vcc, exec, s[12:13]
	s_cbranch_vccz .LBB0_1695

.LBB0_1704:
	v_mov_b32_e32 v23, v173
	v_mov_b32_e32 v25, s45
	v_mov_b32_e32 v26, s46
	v_add_f32_e32 v25, s43, v25
	v_add_f32_e32 v26, s44, v26
	v_add_f32_e32 v25, v25, v26
	v_add_f32_e32 v23, v25, v23
	v_cndmask_b32_e64 v25, 0, 1, s[10:11]
	v_cmp_ne_u32_e64 s[12:13], 1, v25
	s_andn2_b64 vcc, exec, s[10:11]
	s_cbranch_vccz .LBB0_1697

.LBB0_1706:
	v_mov_b32_e32 v21, v175
	v_mov_b32_e32 v25, s33
	v_mov_b32_e32 v26, s34
	v_add_f32_e32 v25, s30, v25
	v_add_f32_e32 v26, s31, v26
	v_add_f32_e32 v25, v25, v26
	v_add_f32_e32 v21, v25, v21
	s_and_b64 vcc, exec, s[12:13]
	s_cbranch_vccz .LBB0_1699

.LBB0_1708:
	v_mov_b32_e32 v23, v177
	v_mov_b32_e32 v25, s79
	v_mov_b32_e32 v26, s80
	v_add_f32_e32 v25, s71, v25
	v_add_f32_e32 v26, s74, v26
	v_add_f32_e32 v25, v25, v26
	v_add_f32_e32 v23, v25, v23
	s_and_saveexec_b64 s[24:25], s[6:7]
	s_cbranch_execz .LBB0_1675
